# speedup vs baseline: 1.0272x; 1.0118x over previous
; __device__ __forceinline__ void gll16(const void* g, const void* l) {
;   const unsigned m = __builtin_amdgcn_readfirstlane((unsigned)(uintptr_t)l);
;   asm volatile("s_mov_b32 m0, %0\n\tglobal_load_lds_dwordx4 %1, off" :: "s"(m), "v"(g) : "memory");
; __global__ __launch_bounds__(NTHR, 2) void k_mega(Params p) {
;   extern __shared__ __attribute__((aligned(16))) char shm[];
;   cg::grid_group grid = cg::this_grid();
;   unsigned* barw = (unsigned*)(p.ws + OFF_BAR);
;   const int wv = __builtin_amdgcn_readfirstlane(threadIdx.x >> 6);
;   if (blockIdx.x == 0) for (int i = ltid(wv); i < XCD_BAR_WORDS; i += NTHR) barw[i] = 0u;
_Z6k_mega6Params:
	s_load_dwordx4 s[36:39], s[0:1], 0x60
	s_load_dwordx8 s[4:11], s[0:1], 0x40
	s_mov_b32 s34, s2
	s_add_u32 s2, s0, 0x70
	s_addc_u32 s3, s1, 0
	s_load_dword s57, s[0:1], 0x70
	s_waitcnt lgkmcnt(0)
	v_writelane_b32 v253, s4, 0
	v_and_b32_e32 v1, 0x3ff, v0
	s_nop 0
	v_writelane_b32 v253, s5, 1
	v_writelane_b32 v253, s6, 2
	v_writelane_b32 v253, s7, 3
	v_writelane_b32 v253, s8, 4
	v_writelane_b32 v253, s9, 5
	v_writelane_b32 v253, s10, 6
	v_writelane_b32 v253, s11, 7
	v_writelane_b32 v253, s2, 8
	v_readfirstlane_b32 s4, v1
	s_nop 0
	v_writelane_b32 v253, s3, 9
	s_add_u32 s2, s38, 0x3e600000
	s_addc_u32 s3, s39, 0
	s_and_b32 s91, s4, 0xffffffc0
	s_lshl_b32 s98, s91, 4
	v_writelane_b32 v253, s4, 10
	s_cmp_lg_u32 s34, 0
	s_cbranch_scc1 .LBB0_10
	v_mbcnt_lo_u32_b32 v2, -1, 0
	v_mbcnt_hi_u32_b32 v2, -1, v2
	s_movk_i32 s4, 0xd80
	v_or_b32_e32 v2, s91, v2
	v_cmp_gt_i32_e32 vcc, s4, v2
	s_and_saveexec_b64 s[4:5], vcc
	s_cbranch_execz .LBB0_9
	v_max_i32_e32 v3, 0xb80, v2
	v_sub_u32_e32 v3, v3, v2
	s_movk_i32 s6, 0x1ff
	v_add_u32_e32 v3, 0x1ff, v3
	v_cmp_lt_u32_e32 vcc, s6, v3
	s_mov_b64 s[8:9], -1
	s_and_saveexec_b64 s[6:7], vcc
	s_cbranch_execz .LBB0_6
	v_lshrrev_b32_e32 v3, 9, v3
	v_add_u32_e32 v6, 1, v3
	v_and_b32_e32 v7, 0xfffffe, v6
	v_add_u32_e32 v3, 0x200, v2
	s_mov_b64 s[8:9], 0
	v_mov_b32_e32 v8, 0
	v_mov_b32_e32 v9, v7
	v_mov_b64_e32 v[4:5], v[2:3]

;   #define LDA(dst,b,h) for(int m=0;m<4;++m)for(int k=0;k<2;++k) \
;     dst[m][k]=*reinterpret_cast<const bf16x8*>((char*)SA(b,h)+lds_byte(wr*64+m*16+fr,k*32+fq*8))
;   #define LDB(dst,b,h) for(int n=0;n<2;++n)for(int k=0;k<2;++k) \
;     dst[n][k]=*reinterpret_cast<const bf16x8*>((char*)SB(b,h)+lds_byte(wc*32+n*16+fr,k*32+fq*8))
;   #define MMA(ai,bj,At,Bt_) do{__builtin_amdgcn_s_setprio(1); \
;     for(int m=0;m<4;++m)for(int n=0;n<2;++n)for(int k=0;k<2;++k) \
;       acc[ai][bj][m][n]=__builtin_amdgcn_mfma_f32_16x16x32_bf16(Bt_[n][k],At[m][k],acc[ai][bj][m][n],0,0,0); \
;     __builtin_amdgcn_s_setprio(0);}while(0)
;   #define WAIT_V(n) asm volatile("s_waitcnt vmcnt(" #n ")":::"memory")
;   #define WAIT_L(n) asm volatile("s_waitcnt lgkmcnt(" #n ")":::"memory")
;   #define BAR __builtin_amdgcn_s_barrier()
;   #define SCHED __builtin_amdgcn_sched_barrier(0)
; __device__ __forceinline__ void gll16(const void* g, const void* l) {
;   const unsigned m = __builtin_amdgcn_readfirstlane((unsigned)(uintptr_t)l);
;   asm volatile("s_mov_b32 m0, %0\n\tglobal_load_lds_dwordx4 %1, off" :: "s"(m), "v"(g) : "memory");
; template <bool TWO, class MID> ...
;     ...
;     LDB(B0,0,0); SCHED; LDA(At,0,0); STAGE_A(SA(1,1),1,t+1);
;     WAIT_L(8); BAR; WAIT_L(0); MMA(0,0,At,B0); BAR; SCHED;
;     LDB(B1,0,1); STAGE_B(SB(0,0),0,t+2);
;     BAR; WAIT_L(0); MMA(0,1,At,B1); BAR;
;     LDA(At,0,1); STAGE_A(SA(0,0),0,t+2);
;     BAR; WAIT_L(0); MMA(1,0,At,B0); BAR; SCHED;
;     STAGE_B(SB(0,1),1,t+2);
;     WAIT_V(6); BAR; MMA(1,1,At,B1); BAR;
.LBB0_169:
	ds_read_b128 v[170:173], v143
	ds_read_b128 v[174:177], v143 offset:1024
	ds_read_b128 v[178:181], v143 offset:2048
	ds_read_b128 v[182:185], v143 offset:3072
	ds_read_b128 v[186:189], v168
	ds_read_b128 v[190:193], v168 offset:1024
	ds_read_b128 v[196:199], v167
	ds_read_b128 v[200:203], v167 offset:1024
	ds_read_b128 v[204:207], v166
	ds_read_b128 v[208:211], v166 offset:1024
	ds_read_b128 v[212:215], v147
	ds_read_b128 v[216:219], v147 offset:1024
	s_add_u32 s17, s0, s12
	s_addc_u32 s18, s1, s13
	s_add_u32 s20, s17, 0x8080080
	s_addc_u32 s21, s18, 0
	s_add_u32 m0, s98, 0xc000
	global_load_lds_dwordx4 v132, s[20:21]
	s_add_u32 m0, s98, 0xe000
	global_load_lds_dwordx4 v130, s[20:21]
	s_waitcnt lgkmcnt(8)
	s_barrier
	s_waitcnt lgkmcnt(0)
	s_setprio 1
	v_mfma_f32_16x16x32_bf16 v[126:129], v[170:173], v[186:189], v[126:129]
	v_mfma_f32_16x16x32_bf16 v[122:125], v[178:181], v[186:189], v[122:125]
	v_mfma_f32_16x16x32_bf16 v[118:121], v[170:173], v[196:199], v[118:121]
	v_mfma_f32_16x16x32_bf16 v[114:117], v[178:181], v[196:199], v[114:117]
	v_mfma_f32_16x16x32_bf16 v[110:113], v[170:173], v[204:207], v[110:113]
	v_mfma_f32_16x16x32_bf16 v[106:109], v[178:181], v[204:207], v[106:109]
	v_mfma_f32_16x16x32_bf16 v[102:105], v[170:173], v[212:215], v[102:105]
	v_mfma_f32_16x16x32_bf16 v[98:101], v[178:181], v[212:215], v[98:101]
	v_mfma_f32_16x16x32_bf16 v[126:129], v[174:177], v[190:193], v[126:129]
	v_mfma_f32_16x16x32_bf16 v[122:125], v[182:185], v[190:193], v[122:125]
	v_mfma_f32_16x16x32_bf16 v[118:121], v[174:177], v[200:203], v[118:121]
	v_mfma_f32_16x16x32_bf16 v[114:117], v[182:185], v[200:203], v[114:117]
	v_mfma_f32_16x16x32_bf16 v[110:113], v[174:177], v[208:211], v[110:113]
	v_mfma_f32_16x16x32_bf16 v[106:109], v[182:185], v[208:211], v[106:109]
	v_mfma_f32_16x16x32_bf16 v[102:105], v[174:177], v[216:219], v[102:105]
	v_mfma_f32_16x16x32_bf16 v[98:101], v[182:185], v[216:219], v[98:101]
	s_setprio 0
	s_barrier
	s_add_u32 s19, s0, s14
	ds_read_b128 v[220:223], v141
	ds_read_b128 v[224:227], v141 offset:1024
	ds_read_b128 v[228:231], v141 offset:2048
	ds_read_b128 v[232:235], v141 offset:3072
	s_addc_u32 s20, s1, s15
	s_add_u32 s26, s19, 0x100
	s_addc_u32 s27, s20, 0
	s_add_u32 m0, s98, 0x10000
	global_load_lds_dwordx4 v132, s[26:27]
	s_add_u32 m0, s98, 0x12000
	global_load_lds_dwordx4 v130, s[26:27]
	s_barrier
	s_waitcnt lgkmcnt(0)
	s_setprio 1
	v_mfma_f32_16x16x32_bf16 v[94:97], v[220:223], v[186:189], v[94:97]
	v_mfma_f32_16x16x32_bf16 v[90:93], v[228:231], v[186:189], v[90:93]
	v_mfma_f32_16x16x32_bf16 v[86:89], v[220:223], v[196:199], v[86:89]
	v_mfma_f32_16x16x32_bf16 v[82:85], v[228:231], v[196:199], v[82:85]
	v_mfma_f32_16x16x32_bf16 v[78:81], v[220:223], v[204:207], v[78:81]
	v_mfma_f32_16x16x32_bf16 v[74:77], v[228:231], v[204:207], v[74:77]
	v_mfma_f32_16x16x32_bf16 v[70:73], v[220:223], v[212:215], v[70:73]
	v_mfma_f32_16x16x32_bf16 v[66:69], v[228:231], v[212:215], v[66:69]
	v_mfma_f32_16x16x32_bf16 v[94:97], v[224:227], v[190:193], v[94:97]
	v_mfma_f32_16x16x32_bf16 v[90:93], v[232:235], v[190:193], v[90:93]
	v_mfma_f32_16x16x32_bf16 v[86:89], v[224:227], v[200:203], v[86:89]
	v_mfma_f32_16x16x32_bf16 v[82:85], v[232:235], v[200:203], v[82:85]
	v_mfma_f32_16x16x32_bf16 v[78:81], v[224:227], v[208:211], v[78:81]
	v_mfma_f32_16x16x32_bf16 v[74:77], v[232:235], v[208:211], v[74:77]
	v_mfma_f32_16x16x32_bf16 v[70:73], v[224:227], v[216:219], v[70:73]
	v_mfma_f32_16x16x32_bf16 v[66:69], v[232:235], v[216:219], v[66:69]
	s_setprio 0
	s_barrier
	ds_read_b128 v[186:189], v168 offset:16384
	ds_read_b128 v[190:193], v168 offset:17408
	ds_read_b128 v[196:199], v167 offset:16384
	ds_read_b128 v[200:203], v167 offset:17408
	ds_read_b128 v[204:207], v166 offset:16384
	ds_read_b128 v[208:211], v166 offset:17408
	ds_read_b128 v[212:215], v147 offset:16384
	ds_read_b128 v[216:219], v147 offset:17408
	s_add_u32 s26, s17, 0x8000100
	s_addc_u32 s27, s18, 0
	s_add_u32 m0, s98, 0x0
	global_load_lds_dwordx4 v132, s[26:27]
	s_add_u32 m0, s98, 0x2000
	global_load_lds_dwordx4 v130, s[26:27]
	s_barrier
	s_waitcnt lgkmcnt(0)
	s_setprio 1
	v_mfma_f32_16x16x32_bf16 v[62:65], v[170:173], v[186:189], v[62:65]
	v_mfma_f32_16x16x32_bf16 v[58:61], v[178:181], v[186:189], v[58:61]
	v_mfma_f32_16x16x32_bf16 v[54:57], v[170:173], v[196:199], v[54:57]
	v_mfma_f32_16x16x32_bf16 v[50:53], v[178:181], v[196:199], v[50:53]
	v_mfma_f32_16x16x32_bf16 v[46:49], v[170:173], v[204:207], v[46:49]
	v_mfma_f32_16x16x32_bf16 v[42:45], v[178:181], v[204:207], v[42:45]
	v_mfma_f32_16x16x32_bf16 v[38:41], v[170:173], v[212:215], v[38:41]
	v_mfma_f32_16x16x32_bf16 v[34:37], v[178:181], v[212:215], v[34:37]
	v_mfma_f32_16x16x32_bf16 v[62:65], v[174:177], v[190:193], v[62:65]
	v_mfma_f32_16x16x32_bf16 v[58:61], v[182:185], v[190:193], v[58:61]
	v_mfma_f32_16x16x32_bf16 v[54:57], v[174:177], v[200:203], v[54:57]
	v_mfma_f32_16x16x32_bf16 v[50:53], v[182:185], v[200:203], v[50:53]
	v_mfma_f32_16x16x32_bf16 v[46:49], v[174:177], v[208:211], v[46:49]
	v_mfma_f32_16x16x32_bf16 v[42:45], v[182:185], v[208:211], v[42:45]
	v_mfma_f32_16x16x32_bf16 v[38:41], v[174:177], v[216:219], v[38:41]
	v_mfma_f32_16x16x32_bf16 v[34:37], v[182:185], v[216:219], v[34:37]
	s_setprio 0
	s_barrier
	s_add_u32 s26, s19, 0x80100
	s_addc_u32 s27, s20, 0
	s_add_u32 m0, s98, 0x14000
	global_load_lds_dwordx4 v132, s[26:27]
	s_add_u32 m0, s98, 0x16000
	global_load_lds_dwordx4 v130, s[26:27]
	s_waitcnt vmcnt(6)
	s_barrier
;   #define LDA(dst,b,h) for(int m=0;m<4;++m)for(int k=0;k<2;++k) \
;     dst[m][k]=*reinterpret_cast<const bf16x8*>((char*)SA(b,h)+lds_byte(wr*64+m*16+fr,k*32+fq*8))
;   #define LDB(dst,b,h) for(int n=0;n<2;++n)for(int k=0;k<2;++k) \
;     dst[n][k]=*reinterpret_cast<const bf16x8*>((char*)SB(b,h)+lds_byte(wc*32+n*16+fr,k*32+fq*8))
;   #define MMA(ai,bj,At,Bt_) do{__builtin_amdgcn_s_setprio(1); \
;     for(int m=0;m<4;++m)for(int n=0;n<2;++n)for(int k=0;k<2;++k) \
;       acc[ai][bj][m][n]=__builtin_amdgcn_mfma_f32_16x16x32_bf16(Bt_[n][k],At[m][k],acc[ai][bj][m][n],0,0,0); \
;     __builtin_amdgcn_s_setprio(0);}while(0)
;   #define WAIT_V(n) asm volatile("s_waitcnt vmcnt(" #n ")":::"memory")
;   #define WAIT_L(n) asm volatile("s_waitcnt lgkmcnt(" #n ")":::"memory")
;   #define BAR __builtin_amdgcn_s_barrier()
;   #define SCHED __builtin_amdgcn_sched_barrier(0)
; template <bool TWO, class MID> ...
;     ...
;     WAIT_V(6); BAR; MMA(1,1,At,B1); BAR;
;     LDB(B0,1,0); SCHED; LDA(At,1,0); STAGE_A(SA(0,1),1,t+2);
;     WAIT_L(8); BAR; WAIT_L(0); MMA(0,0,At,B0); BAR; SCHED;
;     LDB(B1,1,1); STAGE_B(SB(1,0),0,t+3);
;     BAR; WAIT_L(0); MMA(0,1,At,B1); BAR;
;     LDA(At,1,1); STAGE_A(SA(1,0),0,t+3);
;     BAR; WAIT_L(0); MMA(1,0,At,B0); BAR; SCHED;
;     STAGE_B(SB(1,1),1,t+3);
	s_setprio 1
	v_mfma_f32_16x16x32_bf16 v[30:33], v[220:223], v[186:189], v[30:33]
	v_mfma_f32_16x16x32_bf16 v[26:29], v[228:231], v[186:189], v[26:29]
	v_mfma_f32_16x16x32_bf16 v[22:25], v[220:223], v[196:199], v[22:25]
	v_mfma_f32_16x16x32_bf16 v[18:21], v[228:231], v[196:199], v[18:21]
	v_mfma_f32_16x16x32_bf16 v[14:17], v[220:223], v[204:207], v[14:17]
	v_mfma_f32_16x16x32_bf16 v[10:13], v[228:231], v[204:207], v[10:13]
	v_mfma_f32_16x16x32_bf16 v[6:9], v[220:223], v[212:215], v[6:9]
	v_mfma_f32_16x16x32_bf16 v[2:5], v[228:231], v[212:215], v[2:5]
	v_mfma_f32_16x16x32_bf16 v[30:33], v[224:227], v[190:193], v[30:33]
	v_mfma_f32_16x16x32_bf16 v[26:29], v[232:235], v[190:193], v[26:29]
	v_mfma_f32_16x16x32_bf16 v[22:25], v[224:227], v[200:203], v[22:25]
	v_mfma_f32_16x16x32_bf16 v[18:21], v[232:235], v[200:203], v[18:21]
	v_mfma_f32_16x16x32_bf16 v[14:17], v[224:227], v[208:211], v[14:17]
	v_mfma_f32_16x16x32_bf16 v[10:13], v[232:235], v[208:211], v[10:13]
	v_mfma_f32_16x16x32_bf16 v[6:9], v[224:227], v[216:219], v[6:9]
	v_mfma_f32_16x16x32_bf16 v[2:5], v[232:235], v[216:219], v[2:5]
	s_setprio 0
	s_barrier
	ds_read_b128 v[170:173], v137
	ds_read_b128 v[174:177], v137 offset:1024
	ds_read_b128 v[178:181], v137 offset:2048
	ds_read_b128 v[182:185], v137 offset:3072
	ds_read_b128 v[186:189], v168 offset:32768
	ds_read_b128 v[190:193], v168 offset:33792
	ds_read_b128 v[196:199], v167 offset:32768
	ds_read_b128 v[200:203], v167 offset:33792
	ds_read_b128 v[204:207], v166 offset:32768
	ds_read_b128 v[208:211], v166 offset:33792
	ds_read_b128 v[212:215], v147 offset:32768
	ds_read_b128 v[216:219], v147 offset:33792
	s_add_u32 s26, s17, 0x8080100
	s_addc_u32 s27, s18, 0
	s_add_u32 m0, s98, 0x4000
	global_load_lds_dwordx4 v132, s[26:27]
	s_add_u32 m0, s98, 0x6000
	global_load_lds_dwordx4 v130, s[26:27]
	s_waitcnt lgkmcnt(8)
	s_barrier
	s_waitcnt lgkmcnt(0)
	s_setprio 1
	v_mfma_f32_16x16x32_bf16 v[126:129], v[170:173], v[186:189], v[126:129]
	v_mfma_f32_16x16x32_bf16 v[122:125], v[178:181], v[186:189], v[122:125]
	v_mfma_f32_16x16x32_bf16 v[118:121], v[170:173], v[196:199], v[118:121]
	v_mfma_f32_16x16x32_bf16 v[114:117], v[178:181], v[196:199], v[114:117]
	v_mfma_f32_16x16x32_bf16 v[110:113], v[170:173], v[204:207], v[110:113]
	v_mfma_f32_16x16x32_bf16 v[106:109], v[178:181], v[204:207], v[106:109]
	v_mfma_f32_16x16x32_bf16 v[102:105], v[170:173], v[212:215], v[102:105]
	v_mfma_f32_16x16x32_bf16 v[98:101], v[178:181], v[212:215], v[98:101]
	v_mfma_f32_16x16x32_bf16 v[126:129], v[174:177], v[190:193], v[126:129]
	v_mfma_f32_16x16x32_bf16 v[122:125], v[182:185], v[190:193], v[122:125]
	v_mfma_f32_16x16x32_bf16 v[118:121], v[174:177], v[200:203], v[118:121]
	v_mfma_f32_16x16x32_bf16 v[114:117], v[182:185], v[200:203], v[114:117]
	v_mfma_f32_16x16x32_bf16 v[110:113], v[174:177], v[208:211], v[110:113]
	v_mfma_f32_16x16x32_bf16 v[106:109], v[182:185], v[208:211], v[106:109]
	v_mfma_f32_16x16x32_bf16 v[102:105], v[174:177], v[216:219], v[102:105]
	v_mfma_f32_16x16x32_bf16 v[98:101], v[182:185], v[216:219], v[98:101]
	s_setprio 0
	s_barrier
	ds_read_b128 v[220:223], v135
	ds_read_b128 v[224:227], v135 offset:1024
	ds_read_b128 v[228:231], v135 offset:2048
	ds_read_b128 v[232:235], v135 offset:3072
	s_add_u32 s26, s19, 0x180
	s_addc_u32 s27, s20, 0
	s_add_u32 m0, s98, 0x18000
	global_load_lds_dwordx4 v132, s[26:27]
	s_add_u32 m0, s98, 0x1a000
	global_load_lds_dwordx4 v130, s[26:27]
	s_barrier
	s_waitcnt lgkmcnt(0)
	s_setprio 1
	v_mfma_f32_16x16x32_bf16 v[94:97], v[220:223], v[186:189], v[94:97]
	v_mfma_f32_16x16x32_bf16 v[90:93], v[228:231], v[186:189], v[90:93]
	v_mfma_f32_16x16x32_bf16 v[86:89], v[220:223], v[196:199], v[86:89]
	v_mfma_f32_16x16x32_bf16 v[82:85], v[228:231], v[196:199], v[82:85]
	v_mfma_f32_16x16x32_bf16 v[78:81], v[220:223], v[204:207], v[78:81]
	v_mfma_f32_16x16x32_bf16 v[74:77], v[228:231], v[204:207], v[74:77]
	v_mfma_f32_16x16x32_bf16 v[70:73], v[220:223], v[212:215], v[70:73]
	v_mfma_f32_16x16x32_bf16 v[66:69], v[228:231], v[212:215], v[66:69]
	v_mfma_f32_16x16x32_bf16 v[94:97], v[224:227], v[190:193], v[94:97]
	v_mfma_f32_16x16x32_bf16 v[90:93], v[232:235], v[190:193], v[90:93]
	v_mfma_f32_16x16x32_bf16 v[86:89], v[224:227], v[200:203], v[86:89]
	v_mfma_f32_16x16x32_bf16 v[82:85], v[232:235], v[200:203], v[82:85]
	v_mfma_f32_16x16x32_bf16 v[78:81], v[224:227], v[208:211], v[78:81]
	v_mfma_f32_16x16x32_bf16 v[74:77], v[232:235], v[208:211], v[74:77]
	v_mfma_f32_16x16x32_bf16 v[70:73], v[224:227], v[216:219], v[70:73]
	v_mfma_f32_16x16x32_bf16 v[66:69], v[232:235], v[216:219], v[66:69]
	s_setprio 0
	s_barrier
	ds_read_b128 v[186:189], v168 offset:49152
	ds_read_b128 v[190:193], v168 offset:50176
	ds_read_b128 v[196:199], v167 offset:49152
	ds_read_b128 v[200:203], v167 offset:50176
	ds_read_b128 v[204:207], v166 offset:49152
	ds_read_b128 v[208:211], v166 offset:50176
	ds_read_b128 v[212:215], v147 offset:49152
	ds_read_b128 v[216:219], v147 offset:50176
	s_add_u32 s26, s17, 0x8000180
	s_addc_u32 s27, s18, 0
	s_add_u32 m0, s98, 0x8000
	global_load_lds_dwordx4 v132, s[26:27]
	s_add_u32 m0, s98, 0xa000
	global_load_lds_dwordx4 v130, s[26:27]
	s_barrier
;   #define LDA(dst,b,h) for(int m=0;m<4;++m)for(int k=0;k<2;++k) \
;     dst[m][k]=*reinterpret_cast<const bf16x8*>((char*)SA(b,h)+lds_byte(wr*64+m*16+fr,k*32+fq*8))
;   #define LDB(dst,b,h) for(int n=0;n<2;++n)for(int k=0;k<2;++k) \
;     dst[n][k]=*reinterpret_cast<const bf16x8*>((char*)SB(b,h)+lds_byte(wc*32+n*16+fr,k*32+fq*8))
;   #define MMA(ai,bj,At,Bt_) do{__builtin_amdgcn_s_setprio(1); \
;     for(int m=0;m<4;++m)for(int n=0;n<2;++n)for(int k=0;k<2;++k) \
;       acc[ai][bj][m][n]=__builtin_amdgcn_mfma_f32_16x16x32_bf16(Bt_[n][k],At[m][k],acc[ai][bj][m][n],0,0,0); \
;     __builtin_amdgcn_s_setprio(0);}while(0)
;   #define WAIT_V(n) asm volatile("s_waitcnt vmcnt(" #n ")":::"memory")
;   #define WAIT_L(n) asm volatile("s_waitcnt lgkmcnt(" #n ")":::"memory")
;   #define BAR __builtin_amdgcn_s_barrier()
; template <bool TWO, class MID> ...
;     ...
;     STAGE_B(SB(1,1),1,t+3);
;     WAIT_V(6); BAR; MMA(1,1,At,B1); BAR;
;   }
;   { LDB(B0,0,0); LDA(At,0,0); STAGE_A(SA(1,1),1,nt-1);
;     BAR; WAIT_L(0); MMA(0,0,At,B0); BAR;
;     LDB(B1,0,1); BAR; WAIT_L(0); MMA(0,1,At,B1); BAR;
;     LDA(At,0,1); WAIT_V(4); BAR; WAIT_L(0); MMA(1,0,At,B0); MMA(1,1,At,B1); BAR; }
	s_waitcnt lgkmcnt(0)
	s_setprio 1
	v_mfma_f32_16x16x32_bf16 v[62:65], v[170:173], v[186:189], v[62:65]
	v_mfma_f32_16x16x32_bf16 v[58:61], v[178:181], v[186:189], v[58:61]
	v_mfma_f32_16x16x32_bf16 v[54:57], v[170:173], v[196:199], v[54:57]
	v_mfma_f32_16x16x32_bf16 v[50:53], v[178:181], v[196:199], v[50:53]
	v_mfma_f32_16x16x32_bf16 v[46:49], v[170:173], v[204:207], v[46:49]
	v_mfma_f32_16x16x32_bf16 v[42:45], v[178:181], v[204:207], v[42:45]
	v_mfma_f32_16x16x32_bf16 v[38:41], v[170:173], v[212:215], v[38:41]
	v_mfma_f32_16x16x32_bf16 v[34:37], v[178:181], v[212:215], v[34:37]
	v_mfma_f32_16x16x32_bf16 v[62:65], v[174:177], v[190:193], v[62:65]
	v_mfma_f32_16x16x32_bf16 v[58:61], v[182:185], v[190:193], v[58:61]
	v_mfma_f32_16x16x32_bf16 v[54:57], v[174:177], v[200:203], v[54:57]
	v_mfma_f32_16x16x32_bf16 v[50:53], v[182:185], v[200:203], v[50:53]
	v_mfma_f32_16x16x32_bf16 v[46:49], v[174:177], v[208:211], v[46:49]
	v_mfma_f32_16x16x32_bf16 v[42:45], v[182:185], v[208:211], v[42:45]
	v_mfma_f32_16x16x32_bf16 v[38:41], v[174:177], v[216:219], v[38:41]
	v_mfma_f32_16x16x32_bf16 v[34:37], v[182:185], v[216:219], v[34:37]
	s_setprio 0
	s_barrier
	s_add_u32 s18, s19, 0x80180
	s_addc_u32 s19, s20, 0
	s_add_u32 m0, s98, 0x1c000
	global_load_lds_dwordx4 v132, s[18:19]
	s_add_u32 m0, s98, 0x1e000
	global_load_lds_dwordx4 v130, s[18:19]
	s_waitcnt vmcnt(6)
	s_barrier
	s_setprio 1
	v_mfma_f32_16x16x32_bf16 v[30:33], v[220:223], v[186:189], v[30:33]
	v_mfma_f32_16x16x32_bf16 v[26:29], v[228:231], v[186:189], v[26:29]
	v_mfma_f32_16x16x32_bf16 v[22:25], v[220:223], v[196:199], v[22:25]
	v_mfma_f32_16x16x32_bf16 v[18:21], v[228:231], v[196:199], v[18:21]
	v_mfma_f32_16x16x32_bf16 v[14:17], v[220:223], v[204:207], v[14:17]
	v_mfma_f32_16x16x32_bf16 v[10:13], v[228:231], v[204:207], v[10:13]
	v_mfma_f32_16x16x32_bf16 v[6:9], v[220:223], v[212:215], v[6:9]
	v_mfma_f32_16x16x32_bf16 v[2:5], v[228:231], v[212:215], v[2:5]
	v_mfma_f32_16x16x32_bf16 v[30:33], v[224:227], v[190:193], v[30:33]
	v_mfma_f32_16x16x32_bf16 v[26:29], v[232:235], v[190:193], v[26:29]
	v_mfma_f32_16x16x32_bf16 v[22:25], v[224:227], v[200:203], v[22:25]
	v_mfma_f32_16x16x32_bf16 v[18:21], v[232:235], v[200:203], v[18:21]
	v_mfma_f32_16x16x32_bf16 v[14:17], v[224:227], v[208:211], v[14:17]
	v_mfma_f32_16x16x32_bf16 v[10:13], v[232:235], v[208:211], v[10:13]
	v_mfma_f32_16x16x32_bf16 v[6:9], v[224:227], v[216:219], v[6:9]
	v_mfma_f32_16x16x32_bf16 v[2:5], v[232:235], v[216:219], v[2:5]
	s_setprio 0
	s_add_i32 s9, s9, 2
	s_add_u32 s0, s0, 0x100
	s_addc_u32 s1, s1, 0
	s_cmp_lt_u32 s9, 28
	s_barrier
	s_cbranch_scc1 .LBB0_169
	ds_read_b128 v[150:153], v143
	ds_read_b128 v[158:161], v143 offset:1024
	ds_read_b128 v[162:165], v143 offset:2048
	ds_read_b128 v[142:145], v143 offset:3072
	ds_read_b128 v[170:173], v168
	ds_read_b128 v[174:177], v168 offset:1024
	ds_read_b128 v[178:181], v167
	ds_read_b128 v[182:185], v167 offset:1024
	ds_read_b128 v[186:189], v166
	ds_read_b128 v[190:193], v166 offset:1024
	ds_read_b128 v[196:199], v147
	ds_read_b128 v[200:203], v147 offset:1024
	s_add_u32 s0, s11, 0x80f80
	s_addc_u32 s1, s16, 0
	v_lshl_add_u64 v[132:133], s[0:1], 0, v[132:133]
	v_readfirstlane_b32 s9, v148
	s_mov_b32 m0, s9
	global_load_lds_dwordx4 v[132:133], off
	v_lshl_add_u64 v[130:131], s[0:1], 0, v[130:131]
	v_readfirstlane_b32 s0, v156
	s_mov_b32 m0, s0
	global_load_lds_dwordx4 v[130:131], off
	s_barrier
	s_waitcnt lgkmcnt(0)
	s_setprio 1
	v_mfma_f32_16x16x32_bf16 v[126:129], v[150:153], v[170:173], v[126:129]
	v_mfma_f32_16x16x32_bf16 v[122:125], v[162:165], v[170:173], v[122:125]
	v_mfma_f32_16x16x32_bf16 v[114:117], v[162:165], v[178:181], v[114:117]
	v_mfma_f32_16x16x32_bf16 v[106:109], v[162:165], v[186:189], v[106:109]
	v_mfma_f32_16x16x32_bf16 v[98:101], v[162:165], v[196:199], v[98:101]
	v_mfma_f32_16x16x32_bf16 v[126:129], v[158:161], v[174:177], v[126:129]
	v_mfma_f32_16x16x32_bf16 v[122:125], v[142:145], v[174:177], v[122:125]
	v_mfma_f32_16x16x32_bf16 v[118:121], v[150:153], v[178:181], v[118:121]
	v_mfma_f32_16x16x32_bf16 v[114:117], v[142:145], v[182:185], v[114:117]
	v_mfma_f32_16x16x32_bf16 v[110:113], v[150:153], v[186:189], v[110:113]
	v_mfma_f32_16x16x32_bf16 v[106:109], v[142:145], v[190:193], v[106:109]
	v_mfma_f32_16x16x32_bf16 v[102:105], v[150:153], v[196:199], v[102:105]
	v_mfma_f32_16x16x32_bf16 v[130:133], v[142:145], v[200:203], v[98:101]
	v_mfma_f32_16x16x32_bf16 v[118:121], v[158:161], v[182:185], v[118:121]
	v_mfma_f32_16x16x32_bf16 v[110:113], v[158:161], v[190:193], v[110:113]
	v_mfma_f32_16x16x32_bf16 v[102:105], v[158:161], v[200:203], v[102:105]
	s_setprio 0
	s_barrier
	ds_read_b128 v[98:101], v141
	ds_read_b128 v[154:157], v141 offset:1024
	ds_read_b128 v[204:207], v141 offset:2048
	ds_read_b128 v[138:141], v141 offset:3072
	s_barrier
	s_waitcnt lgkmcnt(0)
	s_setprio 1
	v_mfma_f32_16x16x32_bf16 v[86:89], v[98:101], v[178:181], v[86:89]
	v_mfma_f32_16x16x32_bf16 v[82:85], v[204:207], v[178:181], v[82:85]
	v_mfma_f32_16x16x32_bf16 v[70:73], v[98:101], v[196:199], v[70:73]
	v_mfma_f32_16x16x32_bf16 v[66:69], v[204:207], v[196:199], v[66:69]
	v_mfma_f32_16x16x32_bf16 v[94:97], v[98:101], v[170:173], v[94:97]
	v_mfma_f32_16x16x32_bf16 v[90:93], v[204:207], v[170:173], v[90:93]
	v_mfma_f32_16x16x32_bf16 v[86:89], v[154:157], v[182:185], v[86:89]
	v_mfma_f32_16x16x32_bf16 v[82:85], v[138:141], v[182:185], v[82:85]
	v_mfma_f32_16x16x32_bf16 v[78:81], v[98:101], v[186:189], v[78:81]
	v_mfma_f32_16x16x32_bf16 v[74:77], v[204:207], v[186:189], v[74:77]
	v_mfma_f32_16x16x32_bf16 v[70:73], v[154:157], v[200:203], v[70:73]
	v_mfma_f32_16x16x32_bf16 v[66:69], v[138:141], v[200:203], v[66:69]
	v_mfma_f32_16x16x32_bf16 v[94:97], v[154:157], v[174:177], v[94:97]
	v_mfma_f32_16x16x32_bf16 v[170:173], v[138:141], v[174:177], v[90:93]
	v_mfma_f32_16x16x32_bf16 v[174:177], v[154:157], v[190:193], v[78:81]
	v_mfma_f32_16x16x32_bf16 v[178:181], v[138:141], v[190:193], v[74:77]
	s_setprio 0
	s_barrier
;   #define LDA(dst,b,h) for(int m=0;m<4;++m)for(int k=0;k<2;++k) \
;     dst[m][k]=*reinterpret_cast<const bf16x8*>((char*)SA(b,h)+lds_byte(wr*64+m*16+fr,k*32+fq*8))
;   #define LDB(dst,b,h) for(int n=0;n<2;++n)for(int k=0;k<2;++k) \
;     dst[n][k]=*reinterpret_cast<const bf16x8*>((char*)SB(b,h)+lds_byte(wc*32+n*16+fr,k*32+fq*8))
;   #define MMA(ai,bj,At,Bt_) do{__builtin_amdgcn_s_setprio(1); \
;     for(int m=0;m<4;++m)for(int n=0;n<2;++n)for(int k=0;k<2;++k) \
;       acc[ai][bj][m][n]=__builtin_amdgcn_mfma_f32_16x16x32_bf16(Bt_[n][k],At[m][k],acc[ai][bj][m][n],0,0,0); \
;     __builtin_amdgcn_s_setprio(0);}while(0)
;   #define WAIT_V(n) asm volatile("s_waitcnt vmcnt(" #n ")":::"memory")
;   #define WAIT_L(n) asm volatile("s_waitcnt lgkmcnt(" #n ")":::"memory")
;   #define BAR __builtin_amdgcn_s_barrier()
; template <bool TWO, class MID> ...
;     ...
;     BAR; WAIT_L(0); MMA(0,0,At,B0); BAR;
;     LDB(B1,0,1); BAR; WAIT_L(0); MMA(0,1,At,B1); BAR;
;     LDA(At,0,1); WAIT_V(4); BAR; WAIT_L(0); MMA(1,0,At,B0); MMA(1,1,At,B1); BAR; }
;   { LDB(B0,1,0); LDA(At,1,0); WAIT_V(2); BAR; WAIT_L(0); MMA(0,0,At,B0); BAR;
	s_nop 0
	ds_read_b128 v[74:77], v168 offset:16384
	ds_read_b128 v[78:81], v168 offset:17408
	ds_read_b128 v[90:93], v167 offset:16384
	ds_read_b128 v[182:185], v167 offset:17408
	ds_read_b128 v[186:189], v166 offset:16384
	ds_read_b128 v[190:193], v166 offset:17408
	ds_read_b128 v[196:199], v147 offset:16384
	ds_read_b128 v[200:203], v147 offset:17408
	s_waitcnt vmcnt(4)
	s_barrier
	s_waitcnt lgkmcnt(0)
	s_setprio 1
	v_mfma_f32_16x16x32_bf16 v[62:65], v[150:153], v[74:77], v[62:65]
	v_mfma_f32_16x16x32_bf16 v[58:61], v[162:165], v[74:77], v[58:61]
	v_mfma_f32_16x16x32_bf16 v[54:57], v[150:153], v[90:93], v[54:57]
	v_mfma_f32_16x16x32_bf16 v[50:53], v[162:165], v[90:93], v[50:53]
	v_mfma_f32_16x16x32_bf16 v[38:41], v[150:153], v[196:199], v[38:41]
	v_mfma_f32_16x16x32_bf16 v[34:37], v[162:165], v[196:199], v[34:37]
	v_mfma_f32_16x16x32_bf16 v[62:65], v[158:161], v[78:81], v[62:65]
	v_mfma_f32_16x16x32_bf16 v[58:61], v[142:145], v[78:81], v[58:61]
	v_mfma_f32_16x16x32_bf16 v[54:57], v[158:161], v[182:185], v[54:57]
	v_mfma_f32_16x16x32_bf16 v[50:53], v[142:145], v[182:185], v[50:53]
	v_mfma_f32_16x16x32_bf16 v[46:49], v[150:153], v[186:189], v[46:49]
	v_mfma_f32_16x16x32_bf16 v[42:45], v[162:165], v[186:189], v[42:45]
	v_mfma_f32_16x16x32_bf16 v[38:41], v[158:161], v[200:203], v[38:41]
	v_mfma_f32_16x16x32_bf16 v[34:37], v[142:145], v[200:203], v[34:37]
	v_mfma_f32_16x16x32_bf16 v[208:211], v[158:161], v[190:193], v[46:49]
	v_mfma_f32_16x16x32_bf16 v[212:215], v[142:145], v[190:193], v[42:45]
	s_setprio 0
	s_setprio 1
	v_mfma_f32_16x16x32_bf16 v[22:25], v[98:101], v[90:93], v[22:25]
	v_mfma_f32_16x16x32_bf16 v[18:21], v[204:207], v[90:93], v[18:21]
	v_mfma_f32_16x16x32_bf16 v[6:9], v[98:101], v[196:199], v[6:9]
	v_mfma_f32_16x16x32_bf16 v[2:5], v[204:207], v[196:199], v[2:5]
	v_mfma_f32_16x16x32_bf16 v[30:33], v[98:101], v[74:77], v[30:33]
	v_mfma_f32_16x16x32_bf16 v[26:29], v[204:207], v[74:77], v[26:29]
	v_mfma_f32_16x16x32_bf16 v[22:25], v[154:157], v[182:185], v[22:25]
	v_mfma_f32_16x16x32_bf16 v[18:21], v[138:141], v[182:185], v[18:21]
	v_mfma_f32_16x16x32_bf16 v[14:17], v[98:101], v[186:189], v[14:17]
	v_mfma_f32_16x16x32_bf16 v[10:13], v[204:207], v[186:189], v[10:13]
	v_mfma_f32_16x16x32_bf16 v[6:9], v[154:157], v[200:203], v[6:9]
	v_mfma_f32_16x16x32_bf16 v[2:5], v[138:141], v[200:203], v[2:5]
	v_mfma_f32_16x16x32_bf16 v[148:151], v[154:157], v[78:81], v[30:33]
	v_mfma_f32_16x16x32_bf16 v[158:161], v[138:141], v[78:81], v[26:29]
	v_mfma_f32_16x16x32_bf16 v[162:165], v[154:157], v[190:193], v[14:17]
	v_mfma_f32_16x16x32_bf16 v[182:185], v[138:141], v[190:193], v[10:13]
	s_setprio 0
	s_barrier
	s_nop 0
	ds_read_b128 v[10:13], v137
	ds_read_b128 v[14:17], v137 offset:1024
	ds_read_b128 v[152:155], v137 offset:2048
	ds_read_b128 v[186:189], v137 offset:3072
	ds_read_b128 v[26:29], v168 offset:32768
	ds_read_b128 v[30:33], v168 offset:33792
	ds_read_b128 v[42:45], v167 offset:32768
	ds_read_b128 v[46:49], v167 offset:33792
	ds_read_b128 v[190:193], v166 offset:32768
	ds_read_b128 v[196:199], v166 offset:33792
	ds_read_b128 v[200:203], v147 offset:32768
	ds_read_b128 v[204:207], v147 offset:33792
	s_waitcnt vmcnt(2)
	s_barrier
	s_waitcnt lgkmcnt(0)
	s_setprio 1
	v_mfma_f32_16x16x32_bf16 v[74:77], v[10:13], v[26:29], v[126:129]
	v_mfma_f32_16x16x32_bf16 v[142:145], v[14:17], v[30:33], v[74:77]
	v_mfma_f32_16x16x32_bf16 v[74:77], v[152:155], v[26:29], v[122:125]
	v_mfma_f32_16x16x32_bf16 v[138:141], v[186:189], v[30:33], v[74:77]
	v_mfma_f32_16x16x32_bf16 v[74:77], v[10:13], v[42:45], v[118:121]
	v_mfma_f32_16x16x32_bf16 v[126:129], v[14:17], v[46:49], v[74:77]
	v_mfma_f32_16x16x32_bf16 v[74:77], v[152:155], v[42:45], v[114:117]
	v_mfma_f32_16x16x32_bf16 v[122:125], v[186:189], v[46:49], v[74:77]
	v_mfma_f32_16x16x32_bf16 v[74:77], v[10:13], v[190:193], v[110:113]
	v_mfma_f32_16x16x32_bf16 v[98:101], v[14:17], v[196:199], v[74:77]
	v_mfma_f32_16x16x32_bf16 v[74:77], v[152:155], v[190:193], v[106:109]
	v_mfma_f32_16x16x32_bf16 v[90:93], v[186:189], v[196:199], v[74:77]
	v_mfma_f32_16x16x32_bf16 v[74:77], v[10:13], v[200:203], v[102:105]
	v_mfma_f32_16x16x32_bf16 v[78:81], v[14:17], v[204:207], v[74:77]
	v_mfma_f32_16x16x32_bf16 v[74:77], v[152:155], v[200:203], v[130:133]
	v_mfma_f32_16x16x32_bf16 v[74:77], v[186:189], v[204:207], v[74:77]
	s_setprio 0
	s_barrier
;   #define LDA(dst,b,h) for(int m=0;m<4;++m)for(int k=0;k<2;++k) \
;     dst[m][k]=*reinterpret_cast<const bf16x8*>((char*)SA(b,h)+lds_byte(wr*64+m*16+fr,k*32+fq*8))
;   #define LDB(dst,b,h) for(int n=0;n<2;++n)for(int k=0;k<2;++k) \
;     dst[n][k]=*reinterpret_cast<const bf16x8*>((char*)SB(b,h)+lds_byte(wc*32+n*16+fr,k*32+fq*8))
;   #define MMA(ai,bj,At,Bt_) do{__builtin_amdgcn_s_setprio(1); \
;     for(int m=0;m<4;++m)for(int n=0;n<2;++n)for(int k=0;k<2;++k) \
;       acc[ai][bj][m][n]=__builtin_amdgcn_mfma_f32_16x16x32_bf16(Bt_[n][k],At[m][k],acc[ai][bj][m][n],0,0,0); \
;     __builtin_amdgcn_s_setprio(0);}while(0)
;   #define WAIT_V(n) asm volatile("s_waitcnt vmcnt(" #n ")":::"memory")
;   #define WAIT_L(n) asm volatile("s_waitcnt lgkmcnt(" #n ")":::"memory")
;   #define BAR __builtin_amdgcn_s_barrier()
; template <bool TWO, class MID> ...
;     ...
;   { LDB(B0,1,0); LDA(At,1,0); WAIT_V(2); BAR; WAIT_L(0); MMA(0,0,At,B0); BAR;
;     LDB(B1,1,1); WAIT_V(0); BAR; WAIT_L(0); MMA(0,1,At,B1); BAR;
;     LDA(At,1,1); BAR; WAIT_L(0); MMA(1,0,At,B0); MMA(1,1,At,B1); BAR; }
;   if(wr==0)BAR;
	ds_read_b128 v[102:105], v135
	ds_read_b128 v[110:113], v135 offset:1024
	ds_read_b128 v[118:121], v135 offset:2048
	ds_read_b128 v[216:219], v135 offset:3072
	s_waitcnt vmcnt(0)
	s_barrier
	s_waitcnt lgkmcnt(0)
	s_setprio 1
	v_mfma_f32_16x16x32_bf16 v[94:97], v[102:105], v[26:29], v[94:97]
	v_mfma_f32_16x16x32_bf16 v[26:29], v[118:121], v[26:29], v[170:173]
	v_mfma_f32_16x16x32_bf16 v[130:133], v[216:219], v[30:33], v[26:29]
	v_mfma_f32_16x16x32_bf16 v[26:29], v[102:105], v[42:45], v[86:89]
	v_mfma_f32_16x16x32_bf16 v[114:117], v[110:113], v[46:49], v[26:29]
	v_mfma_f32_16x16x32_bf16 v[26:29], v[118:121], v[42:45], v[82:85]
	v_mfma_f32_16x16x32_bf16 v[106:109], v[216:219], v[46:49], v[26:29]
	v_mfma_f32_16x16x32_bf16 v[26:29], v[102:105], v[190:193], v[174:177]
	v_mfma_f32_16x16x32_bf16 v[86:89], v[110:113], v[196:199], v[26:29]
	v_mfma_f32_16x16x32_bf16 v[26:29], v[118:121], v[190:193], v[178:181]
	v_mfma_f32_16x16x32_bf16 v[82:85], v[216:219], v[196:199], v[26:29]
	v_mfma_f32_16x16x32_bf16 v[26:29], v[102:105], v[200:203], v[70:73]
	v_mfma_f32_16x16x32_bf16 v[70:73], v[110:113], v[204:207], v[26:29]
	v_mfma_f32_16x16x32_bf16 v[26:29], v[118:121], v[200:203], v[66:69]
	v_mfma_f32_16x16x32_bf16 v[134:137], v[110:113], v[30:33], v[94:97]
	v_mfma_f32_16x16x32_bf16 v[66:69], v[216:219], v[204:207], v[26:29]
	s_setprio 0
	s_barrier
	ds_read_b128 v[94:97], v168 offset:49152
	ds_read_b128 v[168:171], v168 offset:50176
	ds_read_b128 v[172:175], v167 offset:49152
	ds_read_b128 v[176:179], v167 offset:50176
	ds_read_b128 v[190:193], v166 offset:49152
	ds_read_b128 v[196:199], v166 offset:50176
	ds_read_b128 v[200:203], v147 offset:49152
	ds_read_b128 v[204:207], v147 offset:50176
	s_barrier
	s_waitcnt lgkmcnt(0)
	s_setprio 1
	v_mfma_f32_16x16x32_bf16 v[26:29], v[10:13], v[94:97], v[62:65]
	v_mfma_f32_16x16x32_bf16 v[62:65], v[14:17], v[168:171], v[26:29]
	v_mfma_f32_16x16x32_bf16 v[26:29], v[152:155], v[94:97], v[58:61]
	v_mfma_f32_16x16x32_bf16 v[58:61], v[186:189], v[168:171], v[26:29]
	v_mfma_f32_16x16x32_bf16 v[26:29], v[10:13], v[172:175], v[54:57]
	v_mfma_f32_16x16x32_bf16 v[46:49], v[14:17], v[176:179], v[26:29]
	v_mfma_f32_16x16x32_bf16 v[26:29], v[152:155], v[172:175], v[50:53]
	v_mfma_f32_16x16x32_bf16 v[42:45], v[186:189], v[176:179], v[26:29]
	v_mfma_f32_16x16x32_bf16 v[26:29], v[10:13], v[190:193], v[208:211]
	v_mfma_f32_16x16x32_bf16 v[10:13], v[10:13], v[200:203], v[38:41]
	v_mfma_f32_16x16x32_bf16 v[30:33], v[14:17], v[196:199], v[26:29]
	v_mfma_f32_16x16x32_bf16 v[26:29], v[152:155], v[190:193], v[212:215]
	v_mfma_f32_16x16x32_bf16 v[14:17], v[14:17], v[204:207], v[10:13]
	v_mfma_f32_16x16x32_bf16 v[10:13], v[152:155], v[200:203], v[34:37]
	v_mfma_f32_16x16x32_bf16 v[26:29], v[186:189], v[196:199], v[26:29]
	v_mfma_f32_16x16x32_bf16 v[10:13], v[186:189], v[204:207], v[10:13]
	s_setprio 0
	s_setprio 1
	v_mfma_f32_16x16x32_bf16 v[34:37], v[102:105], v[94:97], v[148:151]
	v_mfma_f32_16x16x32_bf16 v[54:57], v[110:113], v[168:171], v[34:37]
	v_mfma_f32_16x16x32_bf16 v[34:37], v[118:121], v[94:97], v[158:161]
	v_mfma_f32_16x16x32_bf16 v[18:21], v[118:121], v[172:175], v[18:21]
	v_mfma_f32_16x16x32_bf16 v[50:53], v[216:219], v[168:171], v[34:37]
	v_mfma_f32_16x16x32_bf16 v[22:25], v[102:105], v[172:175], v[22:25]
	v_mfma_f32_16x16x32_bf16 v[34:37], v[216:219], v[176:179], v[18:21]
	v_mfma_f32_16x16x32_bf16 v[18:21], v[102:105], v[190:193], v[162:165]
	v_mfma_f32_16x16x32_bf16 v[38:41], v[110:113], v[176:179], v[22:25]
	v_mfma_f32_16x16x32_bf16 v[22:25], v[110:113], v[196:199], v[18:21]
	v_mfma_f32_16x16x32_bf16 v[18:21], v[118:121], v[190:193], v[182:185]
	v_mfma_f32_16x16x32_bf16 v[6:9], v[102:105], v[200:203], v[6:9]
	v_mfma_f32_16x16x32_bf16 v[2:5], v[118:121], v[200:203], v[2:5]
	v_mfma_f32_16x16x32_bf16 v[18:21], v[216:219], v[196:199], v[18:21]
	v_mfma_f32_16x16x32_bf16 v[6:9], v[110:113], v[204:207], v[6:9]
	v_mfma_f32_16x16x32_bf16 v[2:5], v[216:219], v[204:207], v[2:5]
	s_setprio 0
	v_cmp_gt_u32_e32 vcc, s30, v1
	s_barrier
	s_and_saveexec_b64 s[0:1], vcc
	s_cbranch_execz .LBB0_172
	s_barrier

;   #define LDA(dst,b,h) for(int m=0;m<4;++m)for(int k=0;k<2;++k) \
;     dst[m][k]=*reinterpret_cast<const bf16x8*>((char*)SA(b,h)+lds_byte(wr*64+m*16+fr,k*32+fq*8))
;   #define LDB(dst,b,h) for(int n=0;n<2;++n)for(int k=0;k<2;++k) \
;     dst[n][k]=*reinterpret_cast<const bf16x8*>((char*)SB(b,h)+lds_byte(wc*32+n*16+fr,k*32+fq*8))
;   #define MMA(ai,bj,At,Bt_) do{__builtin_amdgcn_s_setprio(1); \
;     for(int m=0;m<4;++m)for(int n=0;n<2;++n)for(int k=0;k<2;++k) \
;       acc[ai][bj][m][n]=__builtin_amdgcn_mfma_f32_16x16x32_bf16(Bt_[n][k],At[m][k],acc[ai][bj][m][n],0,0,0); \
;     __builtin_amdgcn_s_setprio(0);}while(0)
;   #define WAIT_V(n) asm volatile("s_waitcnt vmcnt(" #n ")":::"memory")
;   #define WAIT_L(n) asm volatile("s_waitcnt lgkmcnt(" #n ")":::"memory")
;   #define BAR __builtin_amdgcn_s_barrier()
;   #define SCHED __builtin_amdgcn_sched_barrier(0)
; __device__ __forceinline__ void gll16(const void* g, const void* l) {
;   const unsigned m = __builtin_amdgcn_readfirstlane((unsigned)(uintptr_t)l);
;   asm volatile("s_mov_b32 m0, %0\n\tglobal_load_lds_dwordx4 %1, off" :: "s"(m), "v"(g) : "memory");
; template <bool TWO, class MID> ...
;     ...
;     LDB(B0,0,0); SCHED; LDA(At,0,0); STAGE_A(SA(1,1),1,t+1);
;     WAIT_L(8); BAR; WAIT_L(0); MMA(0,0,At,B0); BAR; SCHED;
;     LDB(B1,0,1); STAGE_B(SB(0,0),0,t+2);
;     BAR; WAIT_L(0); MMA(0,1,At,B1); BAR;
;     LDA(At,0,1); STAGE_A(SA(0,0),0,t+2);
;     BAR; WAIT_L(0); MMA(1,0,At,B0); BAR; SCHED;
;     STAGE_B(SB(0,1),1,t+2);
;     WAIT_V(6); BAR; MMA(1,1,At,B1); BAR;
.LBB0_489:
	ds_read_b128 v[166:169], v149
	ds_read_b128 v[170:173], v149 offset:1024
	ds_read_b128 v[174:177], v149 offset:2048
	ds_read_b128 v[178:181], v149 offset:3072
	ds_read_b128 v[182:185], v141
	ds_read_b128 v[186:189], v141 offset:1024
	ds_read_b128 v[190:193], v139
	ds_read_b128 v[196:199], v139 offset:1024
	ds_read_b128 v[200:203], v137
	ds_read_b128 v[204:207], v137 offset:1024
	ds_read_b128 v[208:211], v135
	ds_read_b128 v[212:215], v135 offset:1024
	s_add_u32 s19, s4, s10
	s_addc_u32 s24, s5, s11
	s_add_u32 s26, s19, 0x36080080
	s_addc_u32 s27, s24, 0
	s_add_u32 m0, s98, 0xc000
	global_load_lds_dwordx4 v132, s[26:27]
	s_add_u32 m0, s98, 0xe000
	global_load_lds_dwordx4 v130, s[26:27]
	s_waitcnt lgkmcnt(8)
	s_barrier
	s_waitcnt lgkmcnt(0)
	s_setprio 1
	v_mfma_f32_16x16x32_bf16 v[126:129], v[166:169], v[182:185], v[126:129]
	v_mfma_f32_16x16x32_bf16 v[122:125], v[174:177], v[182:185], v[122:125]
	v_mfma_f32_16x16x32_bf16 v[118:121], v[166:169], v[190:193], v[118:121]
	v_mfma_f32_16x16x32_bf16 v[114:117], v[174:177], v[190:193], v[114:117]
	v_mfma_f32_16x16x32_bf16 v[110:113], v[166:169], v[200:203], v[110:113]
	v_mfma_f32_16x16x32_bf16 v[106:109], v[174:177], v[200:203], v[106:109]
	v_mfma_f32_16x16x32_bf16 v[102:105], v[166:169], v[208:211], v[102:105]
	v_mfma_f32_16x16x32_bf16 v[98:101], v[174:177], v[208:211], v[98:101]
	v_mfma_f32_16x16x32_bf16 v[126:129], v[170:173], v[186:189], v[126:129]
	v_mfma_f32_16x16x32_bf16 v[122:125], v[178:181], v[186:189], v[122:125]
	v_mfma_f32_16x16x32_bf16 v[118:121], v[170:173], v[196:199], v[118:121]
	v_mfma_f32_16x16x32_bf16 v[114:117], v[178:181], v[196:199], v[114:117]
	v_mfma_f32_16x16x32_bf16 v[110:113], v[170:173], v[204:207], v[110:113]
	v_mfma_f32_16x16x32_bf16 v[106:109], v[178:181], v[204:207], v[106:109]
	v_mfma_f32_16x16x32_bf16 v[102:105], v[170:173], v[212:215], v[102:105]
	v_mfma_f32_16x16x32_bf16 v[98:101], v[178:181], v[212:215], v[98:101]
	s_setprio 0
	s_barrier
	s_add_u32 s25, s4, s16
	ds_read_b128 v[216:219], v147
	ds_read_b128 v[220:223], v147 offset:1024
	ds_read_b128 v[224:227], v147 offset:2048
	ds_read_b128 v[228:231], v147 offset:3072
	s_addc_u32 s26, s5, s17
	s_add_u32 s28, s25, 0x3400100
	s_addc_u32 s29, s26, 0
	s_add_u32 m0, s98, 0x10000
	global_load_lds_dwordx4 v132, s[28:29]
	s_add_u32 m0, s98, 0x12000
	global_load_lds_dwordx4 v130, s[28:29]
	s_barrier
	s_waitcnt lgkmcnt(0)
	s_setprio 1
	v_mfma_f32_16x16x32_bf16 v[94:97], v[216:219], v[182:185], v[94:97]
	v_mfma_f32_16x16x32_bf16 v[90:93], v[224:227], v[182:185], v[90:93]
	v_mfma_f32_16x16x32_bf16 v[86:89], v[216:219], v[190:193], v[86:89]
	v_mfma_f32_16x16x32_bf16 v[82:85], v[224:227], v[190:193], v[82:85]
	v_mfma_f32_16x16x32_bf16 v[78:81], v[216:219], v[200:203], v[78:81]
	v_mfma_f32_16x16x32_bf16 v[74:77], v[224:227], v[200:203], v[74:77]
	v_mfma_f32_16x16x32_bf16 v[70:73], v[216:219], v[208:211], v[70:73]
	v_mfma_f32_16x16x32_bf16 v[66:69], v[224:227], v[208:211], v[66:69]
	v_mfma_f32_16x16x32_bf16 v[94:97], v[220:223], v[186:189], v[94:97]
	v_mfma_f32_16x16x32_bf16 v[90:93], v[228:231], v[186:189], v[90:93]
	v_mfma_f32_16x16x32_bf16 v[86:89], v[220:223], v[196:199], v[86:89]
	v_mfma_f32_16x16x32_bf16 v[82:85], v[228:231], v[196:199], v[82:85]
	v_mfma_f32_16x16x32_bf16 v[78:81], v[220:223], v[204:207], v[78:81]
	v_mfma_f32_16x16x32_bf16 v[74:77], v[228:231], v[204:207], v[74:77]
	v_mfma_f32_16x16x32_bf16 v[70:73], v[220:223], v[212:215], v[70:73]
	v_mfma_f32_16x16x32_bf16 v[66:69], v[228:231], v[212:215], v[66:69]
	s_setprio 0
	s_barrier
	ds_read_b128 v[182:185], v141 offset:16384
	ds_read_b128 v[186:189], v141 offset:17408
	ds_read_b128 v[190:193], v139 offset:16384
	ds_read_b128 v[196:199], v139 offset:17408
	ds_read_b128 v[200:203], v137 offset:16384
	ds_read_b128 v[204:207], v137 offset:17408
	ds_read_b128 v[208:211], v135 offset:16384
	ds_read_b128 v[212:215], v135 offset:17408
	s_add_u32 s28, s19, 0x36000100
	s_addc_u32 s29, s24, 0
	s_add_u32 m0, s98, 0x0
	global_load_lds_dwordx4 v132, s[28:29]
	s_add_u32 m0, s98, 0x2000
	global_load_lds_dwordx4 v130, s[28:29]
	s_barrier
	s_waitcnt lgkmcnt(0)
	s_setprio 1
	v_mfma_f32_16x16x32_bf16 v[62:65], v[166:169], v[182:185], v[62:65]
	v_mfma_f32_16x16x32_bf16 v[58:61], v[174:177], v[182:185], v[58:61]
	v_mfma_f32_16x16x32_bf16 v[54:57], v[166:169], v[190:193], v[54:57]
	v_mfma_f32_16x16x32_bf16 v[50:53], v[174:177], v[190:193], v[50:53]
	v_mfma_f32_16x16x32_bf16 v[46:49], v[166:169], v[200:203], v[46:49]
	v_mfma_f32_16x16x32_bf16 v[42:45], v[174:177], v[200:203], v[42:45]
	v_mfma_f32_16x16x32_bf16 v[38:41], v[166:169], v[208:211], v[38:41]
	v_mfma_f32_16x16x32_bf16 v[34:37], v[174:177], v[208:211], v[34:37]
	v_mfma_f32_16x16x32_bf16 v[62:65], v[170:173], v[186:189], v[62:65]
	v_mfma_f32_16x16x32_bf16 v[58:61], v[178:181], v[186:189], v[58:61]
	v_mfma_f32_16x16x32_bf16 v[54:57], v[170:173], v[196:199], v[54:57]
	v_mfma_f32_16x16x32_bf16 v[50:53], v[178:181], v[196:199], v[50:53]
	v_mfma_f32_16x16x32_bf16 v[46:49], v[170:173], v[204:207], v[46:49]
	v_mfma_f32_16x16x32_bf16 v[42:45], v[178:181], v[204:207], v[42:45]
	v_mfma_f32_16x16x32_bf16 v[38:41], v[170:173], v[212:215], v[38:41]
	v_mfma_f32_16x16x32_bf16 v[34:37], v[178:181], v[212:215], v[34:37]
	s_setprio 0
	s_barrier
	s_add_u32 s28, s25, 0x3480100
	s_addc_u32 s29, s26, 0
	s_add_u32 m0, s98, 0x14000
	global_load_lds_dwordx4 v132, s[28:29]
	s_add_u32 m0, s98, 0x16000
	global_load_lds_dwordx4 v130, s[28:29]
	s_waitcnt vmcnt(6)
	s_barrier
;   #define LDA(dst,b,h) for(int m=0;m<4;++m)for(int k=0;k<2;++k) \
;     dst[m][k]=*reinterpret_cast<const bf16x8*>((char*)SA(b,h)+lds_byte(wr*64+m*16+fr,k*32+fq*8))
;   #define LDB(dst,b,h) for(int n=0;n<2;++n)for(int k=0;k<2;++k) \
;     dst[n][k]=*reinterpret_cast<const bf16x8*>((char*)SB(b,h)+lds_byte(wc*32+n*16+fr,k*32+fq*8))
;   #define MMA(ai,bj,At,Bt_) do{__builtin_amdgcn_s_setprio(1); \
;     for(int m=0;m<4;++m)for(int n=0;n<2;++n)for(int k=0;k<2;++k) \
;       acc[ai][bj][m][n]=__builtin_amdgcn_mfma_f32_16x16x32_bf16(Bt_[n][k],At[m][k],acc[ai][bj][m][n],0,0,0); \
;     __builtin_amdgcn_s_setprio(0);}while(0)
;   #define WAIT_V(n) asm volatile("s_waitcnt vmcnt(" #n ")":::"memory")
;   #define WAIT_L(n) asm volatile("s_waitcnt lgkmcnt(" #n ")":::"memory")
;   #define BAR __builtin_amdgcn_s_barrier()
;   #define SCHED __builtin_amdgcn_sched_barrier(0)
; template <bool TWO, class MID> ...
;     ...
;     WAIT_V(6); BAR; MMA(1,1,At,B1); BAR;
;     LDB(B0,1,0); SCHED; LDA(At,1,0); STAGE_A(SA(0,1),1,t+2);
;     WAIT_L(8); BAR; WAIT_L(0); MMA(0,0,At,B0); BAR; SCHED;
;     LDB(B1,1,1); STAGE_B(SB(1,0),0,t+3);
;     BAR; WAIT_L(0); MMA(0,1,At,B1); BAR;
;     LDA(At,1,1); STAGE_A(SA(1,0),0,t+3);
;     BAR; WAIT_L(0); MMA(1,0,At,B0); BAR; SCHED;
;     STAGE_B(SB(1,1),1,t+3);
	s_setprio 1
	v_mfma_f32_16x16x32_bf16 v[30:33], v[216:219], v[182:185], v[30:33]
	v_mfma_f32_16x16x32_bf16 v[26:29], v[224:227], v[182:185], v[26:29]
	v_mfma_f32_16x16x32_bf16 v[22:25], v[216:219], v[190:193], v[22:25]
	v_mfma_f32_16x16x32_bf16 v[18:21], v[224:227], v[190:193], v[18:21]
	v_mfma_f32_16x16x32_bf16 v[14:17], v[216:219], v[200:203], v[14:17]
	v_mfma_f32_16x16x32_bf16 v[10:13], v[224:227], v[200:203], v[10:13]
	v_mfma_f32_16x16x32_bf16 v[6:9], v[216:219], v[208:211], v[6:9]
	v_mfma_f32_16x16x32_bf16 v[2:5], v[224:227], v[208:211], v[2:5]
	v_mfma_f32_16x16x32_bf16 v[30:33], v[220:223], v[186:189], v[30:33]
	v_mfma_f32_16x16x32_bf16 v[26:29], v[228:231], v[186:189], v[26:29]
	v_mfma_f32_16x16x32_bf16 v[22:25], v[220:223], v[196:199], v[22:25]
	v_mfma_f32_16x16x32_bf16 v[18:21], v[228:231], v[196:199], v[18:21]
	v_mfma_f32_16x16x32_bf16 v[14:17], v[220:223], v[204:207], v[14:17]
	v_mfma_f32_16x16x32_bf16 v[10:13], v[228:231], v[204:207], v[10:13]
	v_mfma_f32_16x16x32_bf16 v[6:9], v[220:223], v[212:215], v[6:9]
	v_mfma_f32_16x16x32_bf16 v[2:5], v[228:231], v[212:215], v[2:5]
	s_setprio 0
	s_barrier
	ds_read_b128 v[166:169], v145
	ds_read_b128 v[170:173], v145 offset:1024
	ds_read_b128 v[174:177], v145 offset:2048
	ds_read_b128 v[178:181], v145 offset:3072
	ds_read_b128 v[182:185], v141 offset:32768
	ds_read_b128 v[186:189], v141 offset:33792
	ds_read_b128 v[190:193], v139 offset:32768
	ds_read_b128 v[196:199], v139 offset:33792
	ds_read_b128 v[200:203], v137 offset:32768
	ds_read_b128 v[204:207], v137 offset:33792
	ds_read_b128 v[208:211], v135 offset:32768
	ds_read_b128 v[212:215], v135 offset:33792
	s_add_u32 s28, s19, 0x36080100
	s_addc_u32 s29, s24, 0
	s_add_u32 m0, s98, 0x4000
	global_load_lds_dwordx4 v132, s[28:29]
	s_add_u32 m0, s98, 0x6000
	global_load_lds_dwordx4 v130, s[28:29]
	s_waitcnt lgkmcnt(8)
	s_barrier
	s_waitcnt lgkmcnt(0)
	s_setprio 1
	v_mfma_f32_16x16x32_bf16 v[126:129], v[166:169], v[182:185], v[126:129]
	v_mfma_f32_16x16x32_bf16 v[122:125], v[174:177], v[182:185], v[122:125]
	v_mfma_f32_16x16x32_bf16 v[118:121], v[166:169], v[190:193], v[118:121]
	v_mfma_f32_16x16x32_bf16 v[114:117], v[174:177], v[190:193], v[114:117]
	v_mfma_f32_16x16x32_bf16 v[110:113], v[166:169], v[200:203], v[110:113]
	v_mfma_f32_16x16x32_bf16 v[106:109], v[174:177], v[200:203], v[106:109]
	v_mfma_f32_16x16x32_bf16 v[102:105], v[166:169], v[208:211], v[102:105]
	v_mfma_f32_16x16x32_bf16 v[98:101], v[174:177], v[208:211], v[98:101]
	v_mfma_f32_16x16x32_bf16 v[126:129], v[170:173], v[186:189], v[126:129]
	v_mfma_f32_16x16x32_bf16 v[122:125], v[178:181], v[186:189], v[122:125]
	v_mfma_f32_16x16x32_bf16 v[118:121], v[170:173], v[196:199], v[118:121]
	v_mfma_f32_16x16x32_bf16 v[114:117], v[178:181], v[196:199], v[114:117]
	v_mfma_f32_16x16x32_bf16 v[110:113], v[170:173], v[204:207], v[110:113]
	v_mfma_f32_16x16x32_bf16 v[106:109], v[178:181], v[204:207], v[106:109]
	v_mfma_f32_16x16x32_bf16 v[102:105], v[170:173], v[212:215], v[102:105]
	v_mfma_f32_16x16x32_bf16 v[98:101], v[178:181], v[212:215], v[98:101]
	s_setprio 0
	s_barrier
	ds_read_b128 v[216:219], v143
	ds_read_b128 v[220:223], v143 offset:1024
	ds_read_b128 v[224:227], v143 offset:2048
	ds_read_b128 v[228:231], v143 offset:3072
	s_add_u32 s28, s25, 0x3400180
	s_addc_u32 s29, s26, 0
	s_add_u32 m0, s98, 0x18000
	global_load_lds_dwordx4 v132, s[28:29]
	s_add_u32 m0, s98, 0x1a000
	global_load_lds_dwordx4 v130, s[28:29]
	s_barrier
	s_waitcnt lgkmcnt(0)
	s_setprio 1
	v_mfma_f32_16x16x32_bf16 v[94:97], v[216:219], v[182:185], v[94:97]
	v_mfma_f32_16x16x32_bf16 v[90:93], v[224:227], v[182:185], v[90:93]
	v_mfma_f32_16x16x32_bf16 v[86:89], v[216:219], v[190:193], v[86:89]
	v_mfma_f32_16x16x32_bf16 v[82:85], v[224:227], v[190:193], v[82:85]
	v_mfma_f32_16x16x32_bf16 v[78:81], v[216:219], v[200:203], v[78:81]
	v_mfma_f32_16x16x32_bf16 v[74:77], v[224:227], v[200:203], v[74:77]
	v_mfma_f32_16x16x32_bf16 v[70:73], v[216:219], v[208:211], v[70:73]
	v_mfma_f32_16x16x32_bf16 v[66:69], v[224:227], v[208:211], v[66:69]
	v_mfma_f32_16x16x32_bf16 v[94:97], v[220:223], v[186:189], v[94:97]
	v_mfma_f32_16x16x32_bf16 v[90:93], v[228:231], v[186:189], v[90:93]
	v_mfma_f32_16x16x32_bf16 v[86:89], v[220:223], v[196:199], v[86:89]
	v_mfma_f32_16x16x32_bf16 v[82:85], v[228:231], v[196:199], v[82:85]
	v_mfma_f32_16x16x32_bf16 v[78:81], v[220:223], v[204:207], v[78:81]
	v_mfma_f32_16x16x32_bf16 v[74:77], v[228:231], v[204:207], v[74:77]
	v_mfma_f32_16x16x32_bf16 v[70:73], v[220:223], v[212:215], v[70:73]
	v_mfma_f32_16x16x32_bf16 v[66:69], v[228:231], v[212:215], v[66:69]
	s_setprio 0
	s_barrier
	ds_read_b128 v[182:185], v141 offset:49152
	ds_read_b128 v[186:189], v141 offset:50176
	ds_read_b128 v[190:193], v139 offset:49152
	ds_read_b128 v[196:199], v139 offset:50176
	ds_read_b128 v[200:203], v137 offset:49152
	ds_read_b128 v[204:207], v137 offset:50176
	ds_read_b128 v[208:211], v135 offset:49152
	ds_read_b128 v[212:215], v135 offset:50176
	s_add_u32 s28, s19, 0x36000180
	s_addc_u32 s29, s24, 0
	s_add_u32 m0, s98, 0x8000
	global_load_lds_dwordx4 v132, s[28:29]
	s_add_u32 m0, s98, 0xa000
	global_load_lds_dwordx4 v130, s[28:29]
	s_barrier
;   #define LDA(dst,b,h) for(int m=0;m<4;++m)for(int k=0;k<2;++k) \
;     dst[m][k]=*reinterpret_cast<const bf16x8*>((char*)SA(b,h)+lds_byte(wr*64+m*16+fr,k*32+fq*8))
;   #define LDB(dst,b,h) for(int n=0;n<2;++n)for(int k=0;k<2;++k) \
;     dst[n][k]=*reinterpret_cast<const bf16x8*>((char*)SB(b,h)+lds_byte(wc*32+n*16+fr,k*32+fq*8))
;   #define MMA(ai,bj,At,Bt_) do{__builtin_amdgcn_s_setprio(1); \
;     for(int m=0;m<4;++m)for(int n=0;n<2;++n)for(int k=0;k<2;++k) \
;       acc[ai][bj][m][n]=__builtin_amdgcn_mfma_f32_16x16x32_bf16(Bt_[n][k],At[m][k],acc[ai][bj][m][n],0,0,0); \
;     __builtin_amdgcn_s_setprio(0);}while(0)
;   #define WAIT_V(n) asm volatile("s_waitcnt vmcnt(" #n ")":::"memory")
;   #define WAIT_L(n) asm volatile("s_waitcnt lgkmcnt(" #n ")":::"memory")
;   #define BAR __builtin_amdgcn_s_barrier()
; template <bool TWO, class MID> ...
;     ...
;     STAGE_B(SB(1,1),1,t+3);
;     WAIT_V(6); BAR; MMA(1,1,At,B1); BAR;
;   }
;   { LDB(B0,0,0); LDA(At,0,0); STAGE_A(SA(1,1),1,nt-1);
;     BAR; WAIT_L(0); MMA(0,0,At,B0); BAR;
;     LDB(B1,0,1); BAR; WAIT_L(0); MMA(0,1,At,B1); BAR;
;     LDA(At,0,1); WAIT_V(4); BAR; WAIT_L(0); MMA(1,0,At,B0); MMA(1,1,At,B1); BAR; }
	s_waitcnt lgkmcnt(0)
	s_setprio 1
	v_mfma_f32_16x16x32_bf16 v[62:65], v[166:169], v[182:185], v[62:65]
	v_mfma_f32_16x16x32_bf16 v[58:61], v[174:177], v[182:185], v[58:61]
	v_mfma_f32_16x16x32_bf16 v[54:57], v[166:169], v[190:193], v[54:57]
	v_mfma_f32_16x16x32_bf16 v[50:53], v[174:177], v[190:193], v[50:53]
	v_mfma_f32_16x16x32_bf16 v[46:49], v[166:169], v[200:203], v[46:49]
	v_mfma_f32_16x16x32_bf16 v[42:45], v[174:177], v[200:203], v[42:45]
	v_mfma_f32_16x16x32_bf16 v[38:41], v[166:169], v[208:211], v[38:41]
	v_mfma_f32_16x16x32_bf16 v[34:37], v[174:177], v[208:211], v[34:37]
	v_mfma_f32_16x16x32_bf16 v[62:65], v[170:173], v[186:189], v[62:65]
	v_mfma_f32_16x16x32_bf16 v[58:61], v[178:181], v[186:189], v[58:61]
	v_mfma_f32_16x16x32_bf16 v[54:57], v[170:173], v[196:199], v[54:57]
	v_mfma_f32_16x16x32_bf16 v[50:53], v[178:181], v[196:199], v[50:53]
	v_mfma_f32_16x16x32_bf16 v[46:49], v[170:173], v[204:207], v[46:49]
	v_mfma_f32_16x16x32_bf16 v[42:45], v[178:181], v[204:207], v[42:45]
	v_mfma_f32_16x16x32_bf16 v[38:41], v[170:173], v[212:215], v[38:41]
	v_mfma_f32_16x16x32_bf16 v[34:37], v[178:181], v[212:215], v[34:37]
	s_setprio 0
	s_barrier
	s_add_u32 s24, s25, 0x3480180
	s_addc_u32 s25, s26, 0
	s_add_u32 m0, s98, 0x1c000
	global_load_lds_dwordx4 v132, s[24:25]
	s_add_u32 m0, s98, 0x1e000
	global_load_lds_dwordx4 v130, s[24:25]
	s_waitcnt vmcnt(6)
	s_barrier
	s_setprio 1
	v_mfma_f32_16x16x32_bf16 v[30:33], v[216:219], v[182:185], v[30:33]
	v_mfma_f32_16x16x32_bf16 v[26:29], v[224:227], v[182:185], v[26:29]
	v_mfma_f32_16x16x32_bf16 v[22:25], v[216:219], v[190:193], v[22:25]
	v_mfma_f32_16x16x32_bf16 v[18:21], v[224:227], v[190:193], v[18:21]
	v_mfma_f32_16x16x32_bf16 v[14:17], v[216:219], v[200:203], v[14:17]
	v_mfma_f32_16x16x32_bf16 v[10:13], v[224:227], v[200:203], v[10:13]
	v_mfma_f32_16x16x32_bf16 v[6:9], v[216:219], v[208:211], v[6:9]
	v_mfma_f32_16x16x32_bf16 v[2:5], v[224:227], v[208:211], v[2:5]
	v_mfma_f32_16x16x32_bf16 v[30:33], v[220:223], v[186:189], v[30:33]
	v_mfma_f32_16x16x32_bf16 v[26:29], v[228:231], v[186:189], v[26:29]
	v_mfma_f32_16x16x32_bf16 v[22:25], v[220:223], v[196:199], v[22:25]
	v_mfma_f32_16x16x32_bf16 v[18:21], v[228:231], v[196:199], v[18:21]
	v_mfma_f32_16x16x32_bf16 v[14:17], v[220:223], v[204:207], v[14:17]
	v_mfma_f32_16x16x32_bf16 v[10:13], v[228:231], v[204:207], v[10:13]
	v_mfma_f32_16x16x32_bf16 v[6:9], v[220:223], v[212:215], v[6:9]
	v_mfma_f32_16x16x32_bf16 v[2:5], v[228:231], v[212:215], v[2:5]
	s_setprio 0
	s_add_i32 s18, s18, 2
	s_add_u32 s4, s4, 0x100
	s_addc_u32 s5, s5, 0
	s_cmp_lt_u32 s18, 28
	s_barrier
	s_cbranch_scc1 .LBB0_489
	ds_read_b128 v[152:155], v149
	ds_read_b128 v[156:159], v149 offset:1024
	ds_read_b128 v[160:163], v149 offset:2048
	ds_read_b128 v[164:167], v149 offset:3072
	ds_read_b128 v[168:171], v141
	ds_read_b128 v[172:175], v141 offset:1024
	ds_read_b128 v[176:179], v139
	ds_read_b128 v[180:183], v139 offset:1024
	ds_read_b128 v[184:187], v137
	ds_read_b128 v[188:191], v137 offset:1024
	ds_read_b128 v[196:199], v135
	ds_read_b128 v[200:203], v135 offset:1024
	s_add_u32 s4, s12, 0x80f80
	s_addc_u32 s5, s13, 0
	v_lshl_add_u64 v[132:133], s[4:5], 0, v[132:133]
	v_readfirstlane_b32 s12, v148
	s_mov_b32 m0, s12
	global_load_lds_dwordx4 v[132:133], off
	v_lshl_add_u64 v[130:131], s[4:5], 0, v[130:131]
	v_readfirstlane_b32 s4, v150
	s_mov_b32 m0, s4
	global_load_lds_dwordx4 v[130:131], off
	s_barrier
	s_waitcnt lgkmcnt(0)
	s_setprio 1
	v_mfma_f32_16x16x32_bf16 v[126:129], v[152:155], v[168:171], v[126:129]
	v_mfma_f32_16x16x32_bf16 v[122:125], v[160:163], v[168:171], v[122:125]
	v_mfma_f32_16x16x32_bf16 v[118:121], v[152:155], v[176:179], v[118:121]
	v_mfma_f32_16x16x32_bf16 v[114:117], v[160:163], v[176:179], v[114:117]
	v_mfma_f32_16x16x32_bf16 v[102:105], v[152:155], v[196:199], v[102:105]
	v_mfma_f32_16x16x32_bf16 v[98:101], v[160:163], v[196:199], v[98:101]
	v_mfma_f32_16x16x32_bf16 v[126:129], v[156:159], v[172:175], v[126:129]
	v_mfma_f32_16x16x32_bf16 v[122:125], v[164:167], v[172:175], v[122:125]
	v_mfma_f32_16x16x32_bf16 v[118:121], v[156:159], v[180:183], v[118:121]
	v_mfma_f32_16x16x32_bf16 v[114:117], v[164:167], v[180:183], v[114:117]
	v_mfma_f32_16x16x32_bf16 v[110:113], v[152:155], v[184:187], v[110:113]
	v_mfma_f32_16x16x32_bf16 v[106:109], v[160:163], v[184:187], v[106:109]
	v_mfma_f32_16x16x32_bf16 v[102:105], v[156:159], v[200:203], v[102:105]
	v_mfma_f32_16x16x32_bf16 v[98:101], v[164:167], v[200:203], v[98:101]
	v_mfma_f32_16x16x32_bf16 v[130:133], v[156:159], v[188:191], v[110:113]
	v_mfma_f32_16x16x32_bf16 v[148:151], v[164:167], v[188:191], v[106:109]
	s_setprio 0
	s_barrier
	s_nop 0
	ds_read_b128 v[106:109], v147
	ds_read_b128 v[110:113], v147 offset:1024
	ds_read_b128 v[204:207], v147 offset:2048
	ds_read_b128 v[208:211], v147 offset:3072
	s_barrier
	s_waitcnt lgkmcnt(0)
	s_setprio 1
	v_mfma_f32_16x16x32_bf16 v[86:89], v[106:109], v[176:179], v[86:89]
	v_mfma_f32_16x16x32_bf16 v[82:85], v[204:207], v[176:179], v[82:85]
	v_mfma_f32_16x16x32_bf16 v[70:73], v[106:109], v[196:199], v[70:73]
	v_mfma_f32_16x16x32_bf16 v[66:69], v[204:207], v[196:199], v[66:69]
	v_mfma_f32_16x16x32_bf16 v[94:97], v[106:109], v[168:171], v[94:97]
	v_mfma_f32_16x16x32_bf16 v[90:93], v[204:207], v[168:171], v[90:93]
	v_mfma_f32_16x16x32_bf16 v[86:89], v[110:113], v[180:183], v[86:89]
	v_mfma_f32_16x16x32_bf16 v[82:85], v[208:211], v[180:183], v[82:85]
	v_mfma_f32_16x16x32_bf16 v[78:81], v[106:109], v[184:187], v[78:81]
	v_mfma_f32_16x16x32_bf16 v[74:77], v[204:207], v[184:187], v[74:77]
	v_mfma_f32_16x16x32_bf16 v[70:73], v[110:113], v[200:203], v[70:73]
	v_mfma_f32_16x16x32_bf16 v[66:69], v[208:211], v[200:203], v[66:69]
	v_mfma_f32_16x16x32_bf16 v[212:215], v[110:113], v[172:175], v[94:97]
	v_mfma_f32_16x16x32_bf16 v[168:171], v[208:211], v[172:175], v[90:93]
	v_mfma_f32_16x16x32_bf16 v[172:175], v[110:113], v[188:191], v[78:81]
	v_mfma_f32_16x16x32_bf16 v[176:179], v[208:211], v[188:191], v[74:77]
	s_setprio 0
	s_barrier
;   #define LDA(dst,b,h) for(int m=0;m<4;++m)for(int k=0;k<2;++k) \
;     dst[m][k]=*reinterpret_cast<const bf16x8*>((char*)SA(b,h)+lds_byte(wr*64+m*16+fr,k*32+fq*8))
;   #define LDB(dst,b,h) for(int n=0;n<2;++n)for(int k=0;k<2;++k) \
;     dst[n][k]=*reinterpret_cast<const bf16x8*>((char*)SB(b,h)+lds_byte(wc*32+n*16+fr,k*32+fq*8))
;   #define MMA(ai,bj,At,Bt_) do{__builtin_amdgcn_s_setprio(1); \
;     for(int m=0;m<4;++m)for(int n=0;n<2;++n)for(int k=0;k<2;++k) \
;       acc[ai][bj][m][n]=__builtin_amdgcn_mfma_f32_16x16x32_bf16(Bt_[n][k],At[m][k],acc[ai][bj][m][n],0,0,0); \
;     __builtin_amdgcn_s_setprio(0);}while(0)
;   #define WAIT_V(n) asm volatile("s_waitcnt vmcnt(" #n ")":::"memory")
;   #define WAIT_L(n) asm volatile("s_waitcnt lgkmcnt(" #n ")":::"memory")
;   #define BAR __builtin_amdgcn_s_barrier()
; template <bool TWO, class MID> ...
;     ...
;     BAR; WAIT_L(0); MMA(0,0,At,B0); BAR;
;     LDB(B1,0,1); BAR; WAIT_L(0); MMA(0,1,At,B1); BAR;
;     LDA(At,0,1); WAIT_V(4); BAR; WAIT_L(0); MMA(1,0,At,B0); MMA(1,1,At,B1); BAR; }
;   { LDB(B0,1,0); LDA(At,1,0); WAIT_V(2); BAR; WAIT_L(0); MMA(0,0,At,B0); BAR;
	s_nop 0
	ds_read_b128 v[74:77], v141 offset:16384
	ds_read_b128 v[78:81], v141 offset:17408
	ds_read_b128 v[90:93], v139 offset:16384
	ds_read_b128 v[94:97], v139 offset:17408
	ds_read_b128 v[180:183], v137 offset:16384
	ds_read_b128 v[184:187], v137 offset:17408
	ds_read_b128 v[188:191], v135 offset:16384
	ds_read_b128 v[196:199], v135 offset:17408
	s_waitcnt vmcnt(4)
	s_barrier
	s_waitcnt lgkmcnt(0)
	s_setprio 1
	v_mfma_f32_16x16x32_bf16 v[62:65], v[152:155], v[74:77], v[62:65]
	v_mfma_f32_16x16x32_bf16 v[58:61], v[160:163], v[74:77], v[58:61]
	v_mfma_f32_16x16x32_bf16 v[54:57], v[152:155], v[90:93], v[54:57]
	v_mfma_f32_16x16x32_bf16 v[50:53], v[160:163], v[90:93], v[50:53]
	v_mfma_f32_16x16x32_bf16 v[38:41], v[152:155], v[188:191], v[38:41]
	v_mfma_f32_16x16x32_bf16 v[34:37], v[160:163], v[188:191], v[34:37]
	v_mfma_f32_16x16x32_bf16 v[62:65], v[156:159], v[78:81], v[62:65]
	v_mfma_f32_16x16x32_bf16 v[58:61], v[164:167], v[78:81], v[58:61]
	v_mfma_f32_16x16x32_bf16 v[54:57], v[156:159], v[94:97], v[54:57]
	v_mfma_f32_16x16x32_bf16 v[50:53], v[164:167], v[94:97], v[50:53]
	v_mfma_f32_16x16x32_bf16 v[46:49], v[152:155], v[180:183], v[46:49]
	v_mfma_f32_16x16x32_bf16 v[42:45], v[160:163], v[180:183], v[42:45]
	v_mfma_f32_16x16x32_bf16 v[38:41], v[156:159], v[196:199], v[38:41]
	v_mfma_f32_16x16x32_bf16 v[34:37], v[164:167], v[196:199], v[34:37]
	v_mfma_f32_16x16x32_bf16 v[200:203], v[156:159], v[184:187], v[46:49]
	v_mfma_f32_16x16x32_bf16 v[216:219], v[164:167], v[184:187], v[42:45]
	s_setprio 0
	s_setprio 1
	v_mfma_f32_16x16x32_bf16 v[22:25], v[106:109], v[90:93], v[22:25]
	v_mfma_f32_16x16x32_bf16 v[18:21], v[204:207], v[90:93], v[18:21]
	v_mfma_f32_16x16x32_bf16 v[6:9], v[106:109], v[188:191], v[6:9]
	v_mfma_f32_16x16x32_bf16 v[2:5], v[204:207], v[188:191], v[2:5]
	v_mfma_f32_16x16x32_bf16 v[30:33], v[106:109], v[74:77], v[30:33]
	v_mfma_f32_16x16x32_bf16 v[26:29], v[204:207], v[74:77], v[26:29]
	v_mfma_f32_16x16x32_bf16 v[22:25], v[110:113], v[94:97], v[22:25]
	v_mfma_f32_16x16x32_bf16 v[18:21], v[208:211], v[94:97], v[18:21]
	v_mfma_f32_16x16x32_bf16 v[14:17], v[106:109], v[180:183], v[14:17]
	v_mfma_f32_16x16x32_bf16 v[10:13], v[204:207], v[180:183], v[10:13]
	v_mfma_f32_16x16x32_bf16 v[6:9], v[110:113], v[196:199], v[6:9]
	v_mfma_f32_16x16x32_bf16 v[2:5], v[208:211], v[196:199], v[2:5]
	v_mfma_f32_16x16x32_bf16 v[152:155], v[110:113], v[78:81], v[30:33]
	v_mfma_f32_16x16x32_bf16 v[156:159], v[208:211], v[78:81], v[26:29]
	v_mfma_f32_16x16x32_bf16 v[160:163], v[110:113], v[184:187], v[14:17]
	v_mfma_f32_16x16x32_bf16 v[164:167], v[208:211], v[184:187], v[10:13]
	s_setprio 0
	s_barrier
	s_nop 0
	ds_read_b128 v[10:13], v145
	ds_read_b128 v[14:17], v145 offset:1024
	ds_read_b128 v[180:183], v145 offset:2048
	ds_read_b128 v[144:147], v145 offset:3072
	ds_read_b128 v[26:29], v141 offset:32768
	ds_read_b128 v[30:33], v141 offset:33792
	ds_read_b128 v[42:45], v139 offset:32768
	ds_read_b128 v[46:49], v139 offset:33792
	ds_read_b128 v[184:187], v137 offset:32768
	ds_read_b128 v[188:191], v137 offset:33792
	ds_read_b128 v[196:199], v135 offset:32768
	ds_read_b128 v[204:207], v135 offset:33792
	s_waitcnt vmcnt(2)
	s_barrier
	s_waitcnt lgkmcnt(0)
	s_setprio 1
	v_mfma_f32_16x16x32_bf16 v[74:77], v[10:13], v[26:29], v[126:129]
	v_mfma_f32_16x16x32_bf16 v[126:129], v[14:17], v[30:33], v[74:77]
	v_mfma_f32_16x16x32_bf16 v[74:77], v[180:183], v[26:29], v[122:125]
	v_mfma_f32_16x16x32_bf16 v[122:125], v[144:147], v[30:33], v[74:77]
	v_mfma_f32_16x16x32_bf16 v[74:77], v[10:13], v[42:45], v[118:121]
	v_mfma_f32_16x16x32_bf16 v[110:113], v[14:17], v[46:49], v[74:77]
	v_mfma_f32_16x16x32_bf16 v[74:77], v[180:183], v[42:45], v[114:117]
	v_mfma_f32_16x16x32_bf16 v[106:109], v[144:147], v[46:49], v[74:77]
	v_mfma_f32_16x16x32_bf16 v[74:77], v[10:13], v[184:187], v[130:133]
	v_mfma_f32_16x16x32_bf16 v[94:97], v[14:17], v[188:191], v[74:77]
	v_mfma_f32_16x16x32_bf16 v[74:77], v[180:183], v[184:187], v[148:151]
	v_mfma_f32_16x16x32_bf16 v[90:93], v[144:147], v[188:191], v[74:77]
	v_mfma_f32_16x16x32_bf16 v[74:77], v[10:13], v[196:199], v[102:105]
	v_mfma_f32_16x16x32_bf16 v[78:81], v[14:17], v[204:207], v[74:77]
	v_mfma_f32_16x16x32_bf16 v[74:77], v[180:183], v[196:199], v[98:101]
	v_mfma_f32_16x16x32_bf16 v[74:77], v[144:147], v[204:207], v[74:77]
	s_setprio 0
	s_barrier
;   #define LDA(dst,b,h) for(int m=0;m<4;++m)for(int k=0;k<2;++k) \
;     dst[m][k]=*reinterpret_cast<const bf16x8*>((char*)SA(b,h)+lds_byte(wr*64+m*16+fr,k*32+fq*8))
;   #define LDB(dst,b,h) for(int n=0;n<2;++n)for(int k=0;k<2;++k) \
;     dst[n][k]=*reinterpret_cast<const bf16x8*>((char*)SB(b,h)+lds_byte(wc*32+n*16+fr,k*32+fq*8))
;   #define MMA(ai,bj,At,Bt_) do{__builtin_amdgcn_s_setprio(1); \
;     for(int m=0;m<4;++m)for(int n=0;n<2;++n)for(int k=0;k<2;++k) \
;       acc[ai][bj][m][n]=__builtin_amdgcn_mfma_f32_16x16x32_bf16(Bt_[n][k],At[m][k],acc[ai][bj][m][n],0,0,0); \
;     __builtin_amdgcn_s_setprio(0);}while(0)
;   #define WAIT_V(n) asm volatile("s_waitcnt vmcnt(" #n ")":::"memory")
;   #define WAIT_L(n) asm volatile("s_waitcnt lgkmcnt(" #n ")":::"memory")
;   #define BAR __builtin_amdgcn_s_barrier()
; template <bool TWO, class MID> ...
;     ...
;   { LDB(B0,1,0); LDA(At,1,0); WAIT_V(2); BAR; WAIT_L(0); MMA(0,0,At,B0); BAR;
;     LDB(B1,1,1); WAIT_V(0); BAR; WAIT_L(0); MMA(0,1,At,B1); BAR;
;     LDA(At,1,1); BAR; WAIT_L(0); MMA(1,0,At,B0); MMA(1,1,At,B1); BAR; }
;   if(wr==0)BAR;
	ds_read_b128 v[130:133], v143
	ds_read_b128 v[148:151], v143 offset:1024
	ds_read_b128 v[208:211], v143 offset:2048
	ds_read_b128 v[220:223], v143 offset:3072
	s_waitcnt vmcnt(0)
	s_barrier
	s_waitcnt lgkmcnt(0)
	s_setprio 1
	v_mfma_f32_16x16x32_bf16 v[98:101], v[130:133], v[26:29], v[212:215]
	v_mfma_f32_16x16x32_bf16 v[26:29], v[208:211], v[26:29], v[168:171]
	v_mfma_f32_16x16x32_bf16 v[114:117], v[220:223], v[30:33], v[26:29]
	v_mfma_f32_16x16x32_bf16 v[26:29], v[130:133], v[42:45], v[86:89]
	v_mfma_f32_16x16x32_bf16 v[102:105], v[148:151], v[46:49], v[26:29]
	v_mfma_f32_16x16x32_bf16 v[26:29], v[208:211], v[42:45], v[82:85]
	v_mfma_f32_16x16x32_bf16 v[118:121], v[148:151], v[30:33], v[98:101]
	v_mfma_f32_16x16x32_bf16 v[98:101], v[220:223], v[46:49], v[26:29]
	v_mfma_f32_16x16x32_bf16 v[26:29], v[130:133], v[184:187], v[172:175]
	v_mfma_f32_16x16x32_bf16 v[86:89], v[148:151], v[188:191], v[26:29]
	v_mfma_f32_16x16x32_bf16 v[26:29], v[208:211], v[184:187], v[176:179]
	v_mfma_f32_16x16x32_bf16 v[82:85], v[220:223], v[188:191], v[26:29]
	v_mfma_f32_16x16x32_bf16 v[26:29], v[130:133], v[196:199], v[70:73]
	v_mfma_f32_16x16x32_bf16 v[70:73], v[148:151], v[204:207], v[26:29]
	v_mfma_f32_16x16x32_bf16 v[26:29], v[208:211], v[196:199], v[66:69]
	v_mfma_f32_16x16x32_bf16 v[66:69], v[220:223], v[204:207], v[26:29]
	s_setprio 0
	s_barrier
	ds_read_b128 v[168:171], v141 offset:49152
	ds_read_b128 v[140:143], v141 offset:50176
	ds_read_b128 v[172:175], v139 offset:49152
	ds_read_b128 v[176:179], v139 offset:50176
	ds_read_b128 v[184:187], v137 offset:49152
	ds_read_b128 v[136:139], v137 offset:50176
	ds_read_b128 v[188:191], v135 offset:49152
	ds_read_b128 v[196:199], v135 offset:50176
	s_barrier
	s_waitcnt lgkmcnt(0)
	s_setprio 1
	v_mfma_f32_16x16x32_bf16 v[26:29], v[10:13], v[168:171], v[62:65]
	v_mfma_f32_16x16x32_bf16 v[62:65], v[14:17], v[140:143], v[26:29]
	v_mfma_f32_16x16x32_bf16 v[26:29], v[180:183], v[168:171], v[58:61]
	v_mfma_f32_16x16x32_bf16 v[58:61], v[144:147], v[140:143], v[26:29]
	v_mfma_f32_16x16x32_bf16 v[26:29], v[10:13], v[172:175], v[54:57]
	v_mfma_f32_16x16x32_bf16 v[46:49], v[14:17], v[176:179], v[26:29]
	v_mfma_f32_16x16x32_bf16 v[26:29], v[180:183], v[172:175], v[50:53]
	v_mfma_f32_16x16x32_bf16 v[42:45], v[144:147], v[176:179], v[26:29]
	v_mfma_f32_16x16x32_bf16 v[26:29], v[10:13], v[184:187], v[200:203]
	v_mfma_f32_16x16x32_bf16 v[10:13], v[10:13], v[188:191], v[38:41]
	v_mfma_f32_16x16x32_bf16 v[30:33], v[14:17], v[136:139], v[26:29]
	v_mfma_f32_16x16x32_bf16 v[26:29], v[180:183], v[184:187], v[216:219]
	v_mfma_f32_16x16x32_bf16 v[14:17], v[14:17], v[196:199], v[10:13]
	v_mfma_f32_16x16x32_bf16 v[10:13], v[180:183], v[188:191], v[34:37]
	v_mfma_f32_16x16x32_bf16 v[26:29], v[144:147], v[136:139], v[26:29]
	v_mfma_f32_16x16x32_bf16 v[10:13], v[144:147], v[196:199], v[10:13]
	s_setprio 0
	s_setprio 1
	v_mfma_f32_16x16x32_bf16 v[34:37], v[130:133], v[168:171], v[152:155]
	v_mfma_f32_16x16x32_bf16 v[54:57], v[148:151], v[140:143], v[34:37]
	v_mfma_f32_16x16x32_bf16 v[34:37], v[208:211], v[168:171], v[156:159]
	v_mfma_f32_16x16x32_bf16 v[18:21], v[208:211], v[172:175], v[18:21]
	v_mfma_f32_16x16x32_bf16 v[50:53], v[220:223], v[140:143], v[34:37]
	v_mfma_f32_16x16x32_bf16 v[22:25], v[130:133], v[172:175], v[22:25]
	v_mfma_f32_16x16x32_bf16 v[34:37], v[220:223], v[176:179], v[18:21]
	v_mfma_f32_16x16x32_bf16 v[18:21], v[130:133], v[184:187], v[160:163]
	v_mfma_f32_16x16x32_bf16 v[38:41], v[148:151], v[176:179], v[22:25]
	v_mfma_f32_16x16x32_bf16 v[22:25], v[148:151], v[136:139], v[18:21]
	v_mfma_f32_16x16x32_bf16 v[18:21], v[208:211], v[184:187], v[164:167]
	v_mfma_f32_16x16x32_bf16 v[6:9], v[130:133], v[188:191], v[6:9]
	v_mfma_f32_16x16x32_bf16 v[2:5], v[208:211], v[188:191], v[2:5]
	v_mfma_f32_16x16x32_bf16 v[18:21], v[220:223], v[136:139], v[18:21]
	v_mfma_f32_16x16x32_bf16 v[6:9], v[148:151], v[196:199], v[6:9]
	v_mfma_f32_16x16x32_bf16 v[2:5], v[220:223], v[196:199], v[2:5]
	s_setprio 0
	v_cmp_gt_u32_e32 vcc, s30, v1
	s_barrier
	s_and_saveexec_b64 s[4:5], vcc
	s_cbranch_execz .LBB0_492
	s_barrier

;   #define LDA(dst,b,h) for(int m=0;m<4;++m)for(int k=0;k<2;++k) \
;     dst[m][k]=*reinterpret_cast<const bf16x8*>((char*)SA(b,h)+lds_byte(wr*64+m*16+fr,k*32+fq*8))
;   #define LDB(dst,b,h) for(int n=0;n<2;++n)for(int k=0;k<2;++k) \
;     dst[n][k]=*reinterpret_cast<const bf16x8*>((char*)SB(b,h)+lds_byte(wc*32+n*16+fr,k*32+fq*8))
;   #define MMA(ai,bj,At,Bt_) do{__builtin_amdgcn_s_setprio(1); \
;     for(int m=0;m<4;++m)for(int n=0;n<2;++n)for(int k=0;k<2;++k) \
;       acc[ai][bj][m][n]=__builtin_amdgcn_mfma_f32_16x16x32_bf16(Bt_[n][k],At[m][k],acc[ai][bj][m][n],0,0,0); \
;     __builtin_amdgcn_s_setprio(0);}while(0)
;   #define WAIT_V(n) asm volatile("s_waitcnt vmcnt(" #n ")":::"memory")
;   #define WAIT_L(n) asm volatile("s_waitcnt lgkmcnt(" #n ")":::"memory")
;   #define BAR __builtin_amdgcn_s_barrier()
;   #define SCHED __builtin_amdgcn_sched_barrier(0)
; __device__ __forceinline__ void gll16(const void* g, const void* l) {
;   const unsigned m = __builtin_amdgcn_readfirstlane((unsigned)(uintptr_t)l);
;   asm volatile("s_mov_b32 m0, %0\n\tglobal_load_lds_dwordx4 %1, off" :: "s"(m), "v"(g) : "memory");
; template <bool TWO, class MID> ...
;     ...
;     LDB(B0,0,0); SCHED; LDA(At,0,0); STAGE_A(SA(1,1),1,t+1);
;     WAIT_L(8); BAR; WAIT_L(0); MMA(0,0,At,B0); BAR; SCHED;
;     LDB(B1,0,1); STAGE_B(SB(0,0),0,t+2);
;     BAR; WAIT_L(0); MMA(0,1,At,B1); BAR;
;     LDA(At,0,1); STAGE_A(SA(0,0),0,t+2);
;     BAR; WAIT_L(0); MMA(1,0,At,B0); BAR; SCHED;
;     STAGE_B(SB(0,1),1,t+2);
;     WAIT_V(6); BAR; MMA(1,1,At,B1); BAR;
.LBB0_562:
	ds_read_b128 v[166:169], v149
	ds_read_b128 v[170:173], v149 offset:1024
	ds_read_b128 v[174:177], v149 offset:2048
	ds_read_b128 v[178:181], v149 offset:3072
	ds_read_b128 v[182:185], v141
	ds_read_b128 v[186:189], v141 offset:1024
	ds_read_b128 v[190:193], v139
	ds_read_b128 v[196:199], v139 offset:1024
	ds_read_b128 v[200:203], v137
	ds_read_b128 v[204:207], v137 offset:1024
	ds_read_b128 v[208:211], v135
	ds_read_b128 v[212:215], v135 offset:1024
	s_add_u32 s23, s4, s12
	s_addc_u32 s24, s5, s13
	s_add_u32 s26, s23, 0x8080080
	s_addc_u32 s27, s24, 0
	s_add_u32 m0, s98, 0xc000
	global_load_lds_dwordx4 v132, s[26:27]
	s_add_u32 m0, s98, 0xe000
	global_load_lds_dwordx4 v130, s[26:27]
	s_waitcnt lgkmcnt(8)
	s_barrier
	s_waitcnt lgkmcnt(0)
	s_setprio 1
	v_mfma_f32_16x16x32_bf16 v[126:129], v[166:169], v[182:185], v[126:129]
	v_mfma_f32_16x16x32_bf16 v[122:125], v[174:177], v[182:185], v[122:125]
	v_mfma_f32_16x16x32_bf16 v[118:121], v[166:169], v[190:193], v[118:121]
	v_mfma_f32_16x16x32_bf16 v[114:117], v[174:177], v[190:193], v[114:117]
	v_mfma_f32_16x16x32_bf16 v[110:113], v[166:169], v[200:203], v[110:113]
	v_mfma_f32_16x16x32_bf16 v[106:109], v[174:177], v[200:203], v[106:109]
	v_mfma_f32_16x16x32_bf16 v[102:105], v[166:169], v[208:211], v[102:105]
	v_mfma_f32_16x16x32_bf16 v[98:101], v[174:177], v[208:211], v[98:101]
	v_mfma_f32_16x16x32_bf16 v[126:129], v[170:173], v[186:189], v[126:129]
	v_mfma_f32_16x16x32_bf16 v[122:125], v[178:181], v[186:189], v[122:125]
	v_mfma_f32_16x16x32_bf16 v[118:121], v[170:173], v[196:199], v[118:121]
	v_mfma_f32_16x16x32_bf16 v[114:117], v[178:181], v[196:199], v[114:117]
	v_mfma_f32_16x16x32_bf16 v[110:113], v[170:173], v[204:207], v[110:113]
	v_mfma_f32_16x16x32_bf16 v[106:109], v[178:181], v[204:207], v[106:109]
	v_mfma_f32_16x16x32_bf16 v[102:105], v[170:173], v[212:215], v[102:105]
	v_mfma_f32_16x16x32_bf16 v[98:101], v[178:181], v[212:215], v[98:101]
	s_setprio 0
	s_barrier
	s_add_u32 s25, s4, s14
	ds_read_b128 v[216:219], v147
	ds_read_b128 v[220:223], v147 offset:1024
	ds_read_b128 v[224:227], v147 offset:2048
	ds_read_b128 v[228:231], v147 offset:3072
	s_addc_u32 s26, s5, s15
	s_add_u32 s28, s25, 0x3c00100
	s_addc_u32 s29, s26, 0
	s_add_u32 m0, s98, 0x10000
	global_load_lds_dwordx4 v132, s[28:29]
	s_add_u32 m0, s98, 0x12000
	global_load_lds_dwordx4 v130, s[28:29]
	s_barrier
	s_waitcnt lgkmcnt(0)
	s_setprio 1
	v_mfma_f32_16x16x32_bf16 v[94:97], v[216:219], v[182:185], v[94:97]
	v_mfma_f32_16x16x32_bf16 v[90:93], v[224:227], v[182:185], v[90:93]
	v_mfma_f32_16x16x32_bf16 v[86:89], v[216:219], v[190:193], v[86:89]
	v_mfma_f32_16x16x32_bf16 v[82:85], v[224:227], v[190:193], v[82:85]
	v_mfma_f32_16x16x32_bf16 v[78:81], v[216:219], v[200:203], v[78:81]
	v_mfma_f32_16x16x32_bf16 v[74:77], v[224:227], v[200:203], v[74:77]
	v_mfma_f32_16x16x32_bf16 v[70:73], v[216:219], v[208:211], v[70:73]
	v_mfma_f32_16x16x32_bf16 v[66:69], v[224:227], v[208:211], v[66:69]
	v_mfma_f32_16x16x32_bf16 v[94:97], v[220:223], v[186:189], v[94:97]
	v_mfma_f32_16x16x32_bf16 v[90:93], v[228:231], v[186:189], v[90:93]
	v_mfma_f32_16x16x32_bf16 v[86:89], v[220:223], v[196:199], v[86:89]
	v_mfma_f32_16x16x32_bf16 v[82:85], v[228:231], v[196:199], v[82:85]
	v_mfma_f32_16x16x32_bf16 v[78:81], v[220:223], v[204:207], v[78:81]
	v_mfma_f32_16x16x32_bf16 v[74:77], v[228:231], v[204:207], v[74:77]
	v_mfma_f32_16x16x32_bf16 v[70:73], v[220:223], v[212:215], v[70:73]
	v_mfma_f32_16x16x32_bf16 v[66:69], v[228:231], v[212:215], v[66:69]
	s_setprio 0
	s_barrier
	ds_read_b128 v[182:185], v141 offset:16384
	ds_read_b128 v[186:189], v141 offset:17408
	ds_read_b128 v[190:193], v139 offset:16384
	ds_read_b128 v[196:199], v139 offset:17408
	ds_read_b128 v[200:203], v137 offset:16384
	ds_read_b128 v[204:207], v137 offset:17408
	ds_read_b128 v[208:211], v135 offset:16384
	ds_read_b128 v[212:215], v135 offset:17408
	s_add_u32 s28, s23, 0x8000100
	s_addc_u32 s29, s24, 0
	s_add_u32 m0, s98, 0x0
	global_load_lds_dwordx4 v132, s[28:29]
	s_add_u32 m0, s98, 0x2000
	global_load_lds_dwordx4 v130, s[28:29]
	s_barrier
	s_waitcnt lgkmcnt(0)
	s_setprio 1
	v_mfma_f32_16x16x32_bf16 v[62:65], v[166:169], v[182:185], v[62:65]
	v_mfma_f32_16x16x32_bf16 v[58:61], v[174:177], v[182:185], v[58:61]
	v_mfma_f32_16x16x32_bf16 v[54:57], v[166:169], v[190:193], v[54:57]
	v_mfma_f32_16x16x32_bf16 v[50:53], v[174:177], v[190:193], v[50:53]
	v_mfma_f32_16x16x32_bf16 v[46:49], v[166:169], v[200:203], v[46:49]
	v_mfma_f32_16x16x32_bf16 v[42:45], v[174:177], v[200:203], v[42:45]
	v_mfma_f32_16x16x32_bf16 v[38:41], v[166:169], v[208:211], v[38:41]
	v_mfma_f32_16x16x32_bf16 v[34:37], v[174:177], v[208:211], v[34:37]
	v_mfma_f32_16x16x32_bf16 v[62:65], v[170:173], v[186:189], v[62:65]
	v_mfma_f32_16x16x32_bf16 v[58:61], v[178:181], v[186:189], v[58:61]
	v_mfma_f32_16x16x32_bf16 v[54:57], v[170:173], v[196:199], v[54:57]
	v_mfma_f32_16x16x32_bf16 v[50:53], v[178:181], v[196:199], v[50:53]
	v_mfma_f32_16x16x32_bf16 v[46:49], v[170:173], v[204:207], v[46:49]
	v_mfma_f32_16x16x32_bf16 v[42:45], v[178:181], v[204:207], v[42:45]
	v_mfma_f32_16x16x32_bf16 v[38:41], v[170:173], v[212:215], v[38:41]
	v_mfma_f32_16x16x32_bf16 v[34:37], v[178:181], v[212:215], v[34:37]
	s_setprio 0
	s_barrier
	s_add_u32 s28, s25, 0x3c80100
	s_addc_u32 s29, s26, 0
	s_add_u32 m0, s98, 0x14000
	global_load_lds_dwordx4 v132, s[28:29]
	s_add_u32 m0, s98, 0x16000
	global_load_lds_dwordx4 v130, s[28:29]
	s_waitcnt vmcnt(6)
	s_barrier
;   #define LDA(dst,b,h) for(int m=0;m<4;++m)for(int k=0;k<2;++k) \
;     dst[m][k]=*reinterpret_cast<const bf16x8*>((char*)SA(b,h)+lds_byte(wr*64+m*16+fr,k*32+fq*8))
;   #define LDB(dst,b,h) for(int n=0;n<2;++n)for(int k=0;k<2;++k) \
;     dst[n][k]=*reinterpret_cast<const bf16x8*>((char*)SB(b,h)+lds_byte(wc*32+n*16+fr,k*32+fq*8))
;   #define MMA(ai,bj,At,Bt_) do{__builtin_amdgcn_s_setprio(1); \
;     for(int m=0;m<4;++m)for(int n=0;n<2;++n)for(int k=0;k<2;++k) \
;       acc[ai][bj][m][n]=__builtin_amdgcn_mfma_f32_16x16x32_bf16(Bt_[n][k],At[m][k],acc[ai][bj][m][n],0,0,0); \
;     __builtin_amdgcn_s_setprio(0);}while(0)
;   #define WAIT_V(n) asm volatile("s_waitcnt vmcnt(" #n ")":::"memory")
;   #define WAIT_L(n) asm volatile("s_waitcnt lgkmcnt(" #n ")":::"memory")
;   #define BAR __builtin_amdgcn_s_barrier()
;   #define SCHED __builtin_amdgcn_sched_barrier(0)
; template <bool TWO, class MID> ...
;     ...
;     WAIT_V(6); BAR; MMA(1,1,At,B1); BAR;
;     LDB(B0,1,0); SCHED; LDA(At,1,0); STAGE_A(SA(0,1),1,t+2);
;     WAIT_L(8); BAR; WAIT_L(0); MMA(0,0,At,B0); BAR; SCHED;
;     LDB(B1,1,1); STAGE_B(SB(1,0),0,t+3);
;     BAR; WAIT_L(0); MMA(0,1,At,B1); BAR;
;     LDA(At,1,1); STAGE_A(SA(1,0),0,t+3);
;     BAR; WAIT_L(0); MMA(1,0,At,B0); BAR; SCHED;
;     STAGE_B(SB(1,1),1,t+3);
	s_setprio 1
	v_mfma_f32_16x16x32_bf16 v[30:33], v[216:219], v[182:185], v[30:33]
	v_mfma_f32_16x16x32_bf16 v[26:29], v[224:227], v[182:185], v[26:29]
	v_mfma_f32_16x16x32_bf16 v[22:25], v[216:219], v[190:193], v[22:25]
	v_mfma_f32_16x16x32_bf16 v[18:21], v[224:227], v[190:193], v[18:21]
	v_mfma_f32_16x16x32_bf16 v[14:17], v[216:219], v[200:203], v[14:17]
	v_mfma_f32_16x16x32_bf16 v[10:13], v[224:227], v[200:203], v[10:13]
	v_mfma_f32_16x16x32_bf16 v[6:9], v[216:219], v[208:211], v[6:9]
	v_mfma_f32_16x16x32_bf16 v[2:5], v[224:227], v[208:211], v[2:5]
	v_mfma_f32_16x16x32_bf16 v[30:33], v[220:223], v[186:189], v[30:33]
	v_mfma_f32_16x16x32_bf16 v[26:29], v[228:231], v[186:189], v[26:29]
	v_mfma_f32_16x16x32_bf16 v[22:25], v[220:223], v[196:199], v[22:25]
	v_mfma_f32_16x16x32_bf16 v[18:21], v[228:231], v[196:199], v[18:21]
	v_mfma_f32_16x16x32_bf16 v[14:17], v[220:223], v[204:207], v[14:17]
	v_mfma_f32_16x16x32_bf16 v[10:13], v[228:231], v[204:207], v[10:13]
	v_mfma_f32_16x16x32_bf16 v[6:9], v[220:223], v[212:215], v[6:9]
	v_mfma_f32_16x16x32_bf16 v[2:5], v[228:231], v[212:215], v[2:5]
	s_setprio 0
	s_barrier
	ds_read_b128 v[166:169], v145
	ds_read_b128 v[170:173], v145 offset:1024
	ds_read_b128 v[174:177], v145 offset:2048
	ds_read_b128 v[178:181], v145 offset:3072
	ds_read_b128 v[182:185], v141 offset:32768
	ds_read_b128 v[186:189], v141 offset:33792
	ds_read_b128 v[190:193], v139 offset:32768
	ds_read_b128 v[196:199], v139 offset:33792
	ds_read_b128 v[200:203], v137 offset:32768
	ds_read_b128 v[204:207], v137 offset:33792
	ds_read_b128 v[208:211], v135 offset:32768
	ds_read_b128 v[212:215], v135 offset:33792
	s_add_u32 s28, s23, 0x8080100
	s_addc_u32 s29, s24, 0
	s_add_u32 m0, s98, 0x4000
	global_load_lds_dwordx4 v132, s[28:29]
	s_add_u32 m0, s98, 0x6000
	global_load_lds_dwordx4 v130, s[28:29]
	s_waitcnt lgkmcnt(8)
	s_barrier
	s_waitcnt lgkmcnt(0)
	s_setprio 1
	v_mfma_f32_16x16x32_bf16 v[126:129], v[166:169], v[182:185], v[126:129]
	v_mfma_f32_16x16x32_bf16 v[122:125], v[174:177], v[182:185], v[122:125]
	v_mfma_f32_16x16x32_bf16 v[118:121], v[166:169], v[190:193], v[118:121]
	v_mfma_f32_16x16x32_bf16 v[114:117], v[174:177], v[190:193], v[114:117]
	v_mfma_f32_16x16x32_bf16 v[110:113], v[166:169], v[200:203], v[110:113]
	v_mfma_f32_16x16x32_bf16 v[106:109], v[174:177], v[200:203], v[106:109]
	v_mfma_f32_16x16x32_bf16 v[102:105], v[166:169], v[208:211], v[102:105]
	v_mfma_f32_16x16x32_bf16 v[98:101], v[174:177], v[208:211], v[98:101]
	v_mfma_f32_16x16x32_bf16 v[126:129], v[170:173], v[186:189], v[126:129]
	v_mfma_f32_16x16x32_bf16 v[122:125], v[178:181], v[186:189], v[122:125]
	v_mfma_f32_16x16x32_bf16 v[118:121], v[170:173], v[196:199], v[118:121]
	v_mfma_f32_16x16x32_bf16 v[114:117], v[178:181], v[196:199], v[114:117]
	v_mfma_f32_16x16x32_bf16 v[110:113], v[170:173], v[204:207], v[110:113]
	v_mfma_f32_16x16x32_bf16 v[106:109], v[178:181], v[204:207], v[106:109]
	v_mfma_f32_16x16x32_bf16 v[102:105], v[170:173], v[212:215], v[102:105]
	v_mfma_f32_16x16x32_bf16 v[98:101], v[178:181], v[212:215], v[98:101]
	s_setprio 0
	s_barrier
	ds_read_b128 v[216:219], v143
	ds_read_b128 v[220:223], v143 offset:1024
	ds_read_b128 v[224:227], v143 offset:2048
	ds_read_b128 v[228:231], v143 offset:3072
	s_add_u32 s28, s25, 0x3c00180
	s_addc_u32 s29, s26, 0
	s_add_u32 m0, s98, 0x18000
	global_load_lds_dwordx4 v132, s[28:29]
	s_add_u32 m0, s98, 0x1a000
	global_load_lds_dwordx4 v130, s[28:29]
	s_barrier
	s_waitcnt lgkmcnt(0)
	s_setprio 1
	v_mfma_f32_16x16x32_bf16 v[94:97], v[216:219], v[182:185], v[94:97]
	v_mfma_f32_16x16x32_bf16 v[90:93], v[224:227], v[182:185], v[90:93]
	v_mfma_f32_16x16x32_bf16 v[86:89], v[216:219], v[190:193], v[86:89]
	v_mfma_f32_16x16x32_bf16 v[82:85], v[224:227], v[190:193], v[82:85]
	v_mfma_f32_16x16x32_bf16 v[78:81], v[216:219], v[200:203], v[78:81]
	v_mfma_f32_16x16x32_bf16 v[74:77], v[224:227], v[200:203], v[74:77]
	v_mfma_f32_16x16x32_bf16 v[70:73], v[216:219], v[208:211], v[70:73]
	v_mfma_f32_16x16x32_bf16 v[66:69], v[224:227], v[208:211], v[66:69]
	v_mfma_f32_16x16x32_bf16 v[94:97], v[220:223], v[186:189], v[94:97]
	v_mfma_f32_16x16x32_bf16 v[90:93], v[228:231], v[186:189], v[90:93]
	v_mfma_f32_16x16x32_bf16 v[86:89], v[220:223], v[196:199], v[86:89]
	v_mfma_f32_16x16x32_bf16 v[82:85], v[228:231], v[196:199], v[82:85]
	v_mfma_f32_16x16x32_bf16 v[78:81], v[220:223], v[204:207], v[78:81]
	v_mfma_f32_16x16x32_bf16 v[74:77], v[228:231], v[204:207], v[74:77]
	v_mfma_f32_16x16x32_bf16 v[70:73], v[220:223], v[212:215], v[70:73]
	v_mfma_f32_16x16x32_bf16 v[66:69], v[228:231], v[212:215], v[66:69]
	s_setprio 0
	s_barrier
	ds_read_b128 v[182:185], v141 offset:49152
	ds_read_b128 v[186:189], v141 offset:50176
	ds_read_b128 v[190:193], v139 offset:49152
	ds_read_b128 v[196:199], v139 offset:50176
	ds_read_b128 v[200:203], v137 offset:49152
	ds_read_b128 v[204:207], v137 offset:50176
	ds_read_b128 v[208:211], v135 offset:49152
	ds_read_b128 v[212:215], v135 offset:50176
	s_add_u32 s28, s23, 0x8000180
	s_addc_u32 s29, s24, 0
	s_add_u32 m0, s98, 0x8000
	global_load_lds_dwordx4 v132, s[28:29]
	s_add_u32 m0, s98, 0xa000
	global_load_lds_dwordx4 v130, s[28:29]
	s_barrier
;   #define LDA(dst,b,h) for(int m=0;m<4;++m)for(int k=0;k<2;++k) \
;     dst[m][k]=*reinterpret_cast<const bf16x8*>((char*)SA(b,h)+lds_byte(wr*64+m*16+fr,k*32+fq*8))
;   #define LDB(dst,b,h) for(int n=0;n<2;++n)for(int k=0;k<2;++k) \
;     dst[n][k]=*reinterpret_cast<const bf16x8*>((char*)SB(b,h)+lds_byte(wc*32+n*16+fr,k*32+fq*8))
;   #define MMA(ai,bj,At,Bt_) do{__builtin_amdgcn_s_setprio(1); \
;     for(int m=0;m<4;++m)for(int n=0;n<2;++n)for(int k=0;k<2;++k) \
;       acc[ai][bj][m][n]=__builtin_amdgcn_mfma_f32_16x16x32_bf16(Bt_[n][k],At[m][k],acc[ai][bj][m][n],0,0,0); \
;     __builtin_amdgcn_s_setprio(0);}while(0)
;   #define WAIT_V(n) asm volatile("s_waitcnt vmcnt(" #n ")":::"memory")
;   #define WAIT_L(n) asm volatile("s_waitcnt lgkmcnt(" #n ")":::"memory")
;   #define BAR __builtin_amdgcn_s_barrier()
; template <bool TWO, class MID> ...
;     ...
;     STAGE_B(SB(1,1),1,t+3);
;     WAIT_V(6); BAR; MMA(1,1,At,B1); BAR;
;   }
;   { LDB(B0,0,0); LDA(At,0,0); STAGE_A(SA(1,1),1,nt-1);
;     BAR; WAIT_L(0); MMA(0,0,At,B0); BAR;
;     LDB(B1,0,1); BAR; WAIT_L(0); MMA(0,1,At,B1); BAR;
;     LDA(At,0,1); WAIT_V(4); BAR; WAIT_L(0); MMA(1,0,At,B0); MMA(1,1,At,B1); BAR; }
	s_waitcnt lgkmcnt(0)
	s_setprio 1
	v_mfma_f32_16x16x32_bf16 v[62:65], v[166:169], v[182:185], v[62:65]
	v_mfma_f32_16x16x32_bf16 v[58:61], v[174:177], v[182:185], v[58:61]
	v_mfma_f32_16x16x32_bf16 v[54:57], v[166:169], v[190:193], v[54:57]
	v_mfma_f32_16x16x32_bf16 v[50:53], v[174:177], v[190:193], v[50:53]
	v_mfma_f32_16x16x32_bf16 v[46:49], v[166:169], v[200:203], v[46:49]
	v_mfma_f32_16x16x32_bf16 v[42:45], v[174:177], v[200:203], v[42:45]
	v_mfma_f32_16x16x32_bf16 v[38:41], v[166:169], v[208:211], v[38:41]
	v_mfma_f32_16x16x32_bf16 v[34:37], v[174:177], v[208:211], v[34:37]
	v_mfma_f32_16x16x32_bf16 v[62:65], v[170:173], v[186:189], v[62:65]
	v_mfma_f32_16x16x32_bf16 v[58:61], v[178:181], v[186:189], v[58:61]
	v_mfma_f32_16x16x32_bf16 v[54:57], v[170:173], v[196:199], v[54:57]
	v_mfma_f32_16x16x32_bf16 v[50:53], v[178:181], v[196:199], v[50:53]
	v_mfma_f32_16x16x32_bf16 v[46:49], v[170:173], v[204:207], v[46:49]
	v_mfma_f32_16x16x32_bf16 v[42:45], v[178:181], v[204:207], v[42:45]
	v_mfma_f32_16x16x32_bf16 v[38:41], v[170:173], v[212:215], v[38:41]
	v_mfma_f32_16x16x32_bf16 v[34:37], v[178:181], v[212:215], v[34:37]
	s_setprio 0
	s_barrier
	s_add_u32 s24, s25, 0x3c80180
	s_addc_u32 s25, s26, 0
	s_add_u32 m0, s98, 0x1c000
	global_load_lds_dwordx4 v132, s[24:25]
	s_add_u32 m0, s98, 0x1e000
	global_load_lds_dwordx4 v130, s[24:25]
	s_waitcnt vmcnt(6)
	s_barrier
	s_setprio 1
	v_mfma_f32_16x16x32_bf16 v[30:33], v[216:219], v[182:185], v[30:33]
	v_mfma_f32_16x16x32_bf16 v[26:29], v[224:227], v[182:185], v[26:29]
	v_mfma_f32_16x16x32_bf16 v[22:25], v[216:219], v[190:193], v[22:25]
	v_mfma_f32_16x16x32_bf16 v[18:21], v[224:227], v[190:193], v[18:21]
	v_mfma_f32_16x16x32_bf16 v[14:17], v[216:219], v[200:203], v[14:17]
	v_mfma_f32_16x16x32_bf16 v[10:13], v[224:227], v[200:203], v[10:13]
	v_mfma_f32_16x16x32_bf16 v[6:9], v[216:219], v[208:211], v[6:9]
	v_mfma_f32_16x16x32_bf16 v[2:5], v[224:227], v[208:211], v[2:5]
	v_mfma_f32_16x16x32_bf16 v[30:33], v[220:223], v[186:189], v[30:33]
	v_mfma_f32_16x16x32_bf16 v[26:29], v[228:231], v[186:189], v[26:29]
	v_mfma_f32_16x16x32_bf16 v[22:25], v[220:223], v[196:199], v[22:25]
	v_mfma_f32_16x16x32_bf16 v[18:21], v[228:231], v[196:199], v[18:21]
	v_mfma_f32_16x16x32_bf16 v[14:17], v[220:223], v[204:207], v[14:17]
	v_mfma_f32_16x16x32_bf16 v[10:13], v[228:231], v[204:207], v[10:13]
	v_mfma_f32_16x16x32_bf16 v[6:9], v[220:223], v[212:215], v[6:9]
	v_mfma_f32_16x16x32_bf16 v[2:5], v[228:231], v[212:215], v[2:5]
	s_setprio 0
	s_add_i32 s22, s22, 2
	s_add_u32 s4, s4, 0x100
	s_addc_u32 s5, s5, 0
	s_cmp_lt_u32 s22, 28
	s_barrier
	s_cbranch_scc1 .LBB0_562
	ds_read_b128 v[152:155], v149
	ds_read_b128 v[156:159], v149 offset:1024
	ds_read_b128 v[160:163], v149 offset:2048
	ds_read_b128 v[164:167], v149 offset:3072
	ds_read_b128 v[168:171], v141
	ds_read_b128 v[172:175], v141 offset:1024
	ds_read_b128 v[176:179], v139
	ds_read_b128 v[180:183], v139 offset:1024
	ds_read_b128 v[184:187], v137
	ds_read_b128 v[188:191], v137 offset:1024
	ds_read_b128 v[196:199], v135
	ds_read_b128 v[200:203], v135 offset:1024
	s_add_u32 s4, s19, 0x80f80
	s_addc_u32 s5, s21, 0
	v_lshl_add_u64 v[132:133], s[4:5], 0, v[132:133]
	v_readfirstlane_b32 s12, v148
	s_mov_b32 m0, s12
	global_load_lds_dwordx4 v[132:133], off
	v_lshl_add_u64 v[130:131], s[4:5], 0, v[130:131]
	v_readfirstlane_b32 s4, v150
	s_mov_b32 m0, s4
	global_load_lds_dwordx4 v[130:131], off
	s_barrier
	s_waitcnt lgkmcnt(0)
	s_setprio 1
	v_mfma_f32_16x16x32_bf16 v[126:129], v[152:155], v[168:171], v[126:129]
	v_mfma_f32_16x16x32_bf16 v[122:125], v[160:163], v[168:171], v[122:125]
	v_mfma_f32_16x16x32_bf16 v[114:117], v[160:163], v[176:179], v[114:117]
	v_mfma_f32_16x16x32_bf16 v[106:109], v[160:163], v[184:187], v[106:109]
	v_mfma_f32_16x16x32_bf16 v[98:101], v[160:163], v[196:199], v[98:101]
	v_mfma_f32_16x16x32_bf16 v[126:129], v[156:159], v[172:175], v[126:129]
	v_mfma_f32_16x16x32_bf16 v[122:125], v[164:167], v[172:175], v[122:125]
	v_mfma_f32_16x16x32_bf16 v[118:121], v[152:155], v[176:179], v[118:121]
	v_mfma_f32_16x16x32_bf16 v[114:117], v[164:167], v[180:183], v[114:117]
	v_mfma_f32_16x16x32_bf16 v[110:113], v[152:155], v[184:187], v[110:113]
	v_mfma_f32_16x16x32_bf16 v[106:109], v[164:167], v[188:191], v[106:109]
	v_mfma_f32_16x16x32_bf16 v[102:105], v[152:155], v[196:199], v[102:105]
	v_mfma_f32_16x16x32_bf16 v[98:101], v[164:167], v[200:203], v[98:101]
	v_mfma_f32_16x16x32_bf16 v[130:133], v[156:159], v[180:183], v[118:121]
	v_mfma_f32_16x16x32_bf16 v[148:151], v[156:159], v[188:191], v[110:113]
	v_mfma_f32_16x16x32_bf16 v[204:207], v[156:159], v[200:203], v[102:105]
	s_setprio 0
	s_barrier
	s_nop 0
	ds_read_b128 v[102:105], v147
	ds_read_b128 v[110:113], v147 offset:1024
	ds_read_b128 v[118:121], v147 offset:2048
	ds_read_b128 v[208:211], v147 offset:3072
	s_barrier
	s_waitcnt lgkmcnt(0)
	s_setprio 1
	v_mfma_f32_16x16x32_bf16 v[90:93], v[118:121], v[168:171], v[90:93]
	v_mfma_f32_16x16x32_bf16 v[82:85], v[118:121], v[176:179], v[82:85]
	v_mfma_f32_16x16x32_bf16 v[74:77], v[118:121], v[184:187], v[74:77]
	v_mfma_f32_16x16x32_bf16 v[66:69], v[118:121], v[196:199], v[66:69]
	v_mfma_f32_16x16x32_bf16 v[94:97], v[102:105], v[168:171], v[94:97]
	v_mfma_f32_16x16x32_bf16 v[90:93], v[208:211], v[172:175], v[90:93]
	v_mfma_f32_16x16x32_bf16 v[86:89], v[102:105], v[176:179], v[86:89]
	v_mfma_f32_16x16x32_bf16 v[82:85], v[208:211], v[180:183], v[82:85]
	v_mfma_f32_16x16x32_bf16 v[78:81], v[102:105], v[184:187], v[78:81]
	v_mfma_f32_16x16x32_bf16 v[74:77], v[208:211], v[188:191], v[74:77]
	v_mfma_f32_16x16x32_bf16 v[70:73], v[102:105], v[196:199], v[70:73]
	v_mfma_f32_16x16x32_bf16 v[66:69], v[208:211], v[200:203], v[66:69]
	v_mfma_f32_16x16x32_bf16 v[212:215], v[110:113], v[172:175], v[94:97]
	v_mfma_f32_16x16x32_bf16 v[168:171], v[110:113], v[180:183], v[86:89]
	v_mfma_f32_16x16x32_bf16 v[172:175], v[110:113], v[188:191], v[78:81]
	v_mfma_f32_16x16x32_bf16 v[176:179], v[110:113], v[200:203], v[70:73]
	s_setprio 0
	s_barrier
;   #define LDA(dst,b,h) for(int m=0;m<4;++m)for(int k=0;k<2;++k) \
;     dst[m][k]=*reinterpret_cast<const bf16x8*>((char*)SA(b,h)+lds_byte(wr*64+m*16+fr,k*32+fq*8))
;   #define LDB(dst,b,h) for(int n=0;n<2;++n)for(int k=0;k<2;++k) \
;     dst[n][k]=*reinterpret_cast<const bf16x8*>((char*)SB(b,h)+lds_byte(wc*32+n*16+fr,k*32+fq*8))
;   #define MMA(ai,bj,At,Bt_) do{__builtin_amdgcn_s_setprio(1); \
;     for(int m=0;m<4;++m)for(int n=0;n<2;++n)for(int k=0;k<2;++k) \
;       acc[ai][bj][m][n]=__builtin_amdgcn_mfma_f32_16x16x32_bf16(Bt_[n][k],At[m][k],acc[ai][bj][m][n],0,0,0); \
;     __builtin_amdgcn_s_setprio(0);}while(0)
;   #define WAIT_V(n) asm volatile("s_waitcnt vmcnt(" #n ")":::"memory")
;   #define WAIT_L(n) asm volatile("s_waitcnt lgkmcnt(" #n ")":::"memory")
;   #define BAR __builtin_amdgcn_s_barrier()
; template <bool TWO, class MID> ...
;     ...
;     BAR; WAIT_L(0); MMA(0,0,At,B0); BAR;
;     LDB(B1,0,1); BAR; WAIT_L(0); MMA(0,1,At,B1); BAR;
;     LDA(At,0,1); WAIT_V(4); BAR; WAIT_L(0); MMA(1,0,At,B0); MMA(1,1,At,B1); BAR; }
;   { LDB(B0,1,0); LDA(At,1,0); WAIT_V(2); BAR; WAIT_L(0); MMA(0,0,At,B0); BAR;
	s_nop 0
	ds_read_b128 v[70:73], v141 offset:16384
	ds_read_b128 v[78:81], v141 offset:17408
	ds_read_b128 v[86:89], v139 offset:16384
	ds_read_b128 v[94:97], v139 offset:17408
	ds_read_b128 v[180:183], v137 offset:16384
	ds_read_b128 v[184:187], v137 offset:17408
	ds_read_b128 v[188:191], v135 offset:16384
	ds_read_b128 v[196:199], v135 offset:17408
	s_waitcnt vmcnt(4)
	s_barrier
	s_waitcnt lgkmcnt(0)
	s_setprio 1
	v_mfma_f32_16x16x32_bf16 v[62:65], v[152:155], v[70:73], v[62:65]
	v_mfma_f32_16x16x32_bf16 v[58:61], v[160:163], v[70:73], v[58:61]
	v_mfma_f32_16x16x32_bf16 v[54:57], v[152:155], v[86:89], v[54:57]
	v_mfma_f32_16x16x32_bf16 v[50:53], v[160:163], v[86:89], v[50:53]
	v_mfma_f32_16x16x32_bf16 v[38:41], v[152:155], v[188:191], v[38:41]
	v_mfma_f32_16x16x32_bf16 v[34:37], v[160:163], v[188:191], v[34:37]
	v_mfma_f32_16x16x32_bf16 v[62:65], v[156:159], v[78:81], v[62:65]
	v_mfma_f32_16x16x32_bf16 v[58:61], v[164:167], v[78:81], v[58:61]
	v_mfma_f32_16x16x32_bf16 v[54:57], v[156:159], v[94:97], v[54:57]
	v_mfma_f32_16x16x32_bf16 v[50:53], v[164:167], v[94:97], v[50:53]
	v_mfma_f32_16x16x32_bf16 v[46:49], v[152:155], v[180:183], v[46:49]
	v_mfma_f32_16x16x32_bf16 v[42:45], v[160:163], v[180:183], v[42:45]
	v_mfma_f32_16x16x32_bf16 v[38:41], v[156:159], v[196:199], v[38:41]
	v_mfma_f32_16x16x32_bf16 v[34:37], v[164:167], v[196:199], v[34:37]
	v_mfma_f32_16x16x32_bf16 v[200:203], v[156:159], v[184:187], v[46:49]
	v_mfma_f32_16x16x32_bf16 v[216:219], v[164:167], v[184:187], v[42:45]
	s_setprio 0
	s_setprio 1
	v_mfma_f32_16x16x32_bf16 v[22:25], v[102:105], v[86:89], v[22:25]
	v_mfma_f32_16x16x32_bf16 v[18:21], v[118:121], v[86:89], v[18:21]
	v_mfma_f32_16x16x32_bf16 v[6:9], v[102:105], v[188:191], v[6:9]
	v_mfma_f32_16x16x32_bf16 v[2:5], v[118:121], v[188:191], v[2:5]
	v_mfma_f32_16x16x32_bf16 v[30:33], v[102:105], v[70:73], v[30:33]
	v_mfma_f32_16x16x32_bf16 v[26:29], v[118:121], v[70:73], v[26:29]
	v_mfma_f32_16x16x32_bf16 v[22:25], v[110:113], v[94:97], v[22:25]
	v_mfma_f32_16x16x32_bf16 v[18:21], v[208:211], v[94:97], v[18:21]
	v_mfma_f32_16x16x32_bf16 v[14:17], v[102:105], v[180:183], v[14:17]
	v_mfma_f32_16x16x32_bf16 v[10:13], v[118:121], v[180:183], v[10:13]
	v_mfma_f32_16x16x32_bf16 v[6:9], v[110:113], v[196:199], v[6:9]
	v_mfma_f32_16x16x32_bf16 v[2:5], v[208:211], v[196:199], v[2:5]
	v_mfma_f32_16x16x32_bf16 v[152:155], v[110:113], v[78:81], v[30:33]
	v_mfma_f32_16x16x32_bf16 v[156:159], v[208:211], v[78:81], v[26:29]
	v_mfma_f32_16x16x32_bf16 v[160:163], v[110:113], v[184:187], v[14:17]
	v_mfma_f32_16x16x32_bf16 v[164:167], v[208:211], v[184:187], v[10:13]
	s_setprio 0
	s_barrier
	s_nop 0
	ds_read_b128 v[10:13], v145
	ds_read_b128 v[14:17], v145 offset:1024
	ds_read_b128 v[180:183], v145 offset:2048
	ds_read_b128 v[144:147], v145 offset:3072
	ds_read_b128 v[26:29], v141 offset:32768
	ds_read_b128 v[30:33], v141 offset:33792
	ds_read_b128 v[42:45], v139 offset:32768
	ds_read_b128 v[46:49], v139 offset:33792
	ds_read_b128 v[184:187], v137 offset:32768
	ds_read_b128 v[188:191], v137 offset:33792
	ds_read_b128 v[196:199], v135 offset:32768
	ds_read_b128 v[208:211], v135 offset:33792
	s_waitcnt vmcnt(2)
	s_barrier
	s_waitcnt lgkmcnt(0)
	s_setprio 1
	v_mfma_f32_16x16x32_bf16 v[70:73], v[10:13], v[26:29], v[126:129]
	v_mfma_f32_16x16x32_bf16 v[126:129], v[14:17], v[30:33], v[70:73]
	v_mfma_f32_16x16x32_bf16 v[70:73], v[180:183], v[26:29], v[122:125]
	v_mfma_f32_16x16x32_bf16 v[118:121], v[144:147], v[30:33], v[70:73]
	v_mfma_f32_16x16x32_bf16 v[70:73], v[10:13], v[42:45], v[130:133]
	v_mfma_f32_16x16x32_bf16 v[110:113], v[14:17], v[46:49], v[70:73]
	v_mfma_f32_16x16x32_bf16 v[70:73], v[180:183], v[42:45], v[114:117]
	v_mfma_f32_16x16x32_bf16 v[102:105], v[144:147], v[46:49], v[70:73]
	v_mfma_f32_16x16x32_bf16 v[70:73], v[10:13], v[184:187], v[148:151]
	v_mfma_f32_16x16x32_bf16 v[94:97], v[14:17], v[188:191], v[70:73]
	v_mfma_f32_16x16x32_bf16 v[70:73], v[180:183], v[184:187], v[106:109]
	v_mfma_f32_16x16x32_bf16 v[86:89], v[144:147], v[188:191], v[70:73]
	v_mfma_f32_16x16x32_bf16 v[70:73], v[10:13], v[196:199], v[204:207]
	v_mfma_f32_16x16x32_bf16 v[78:81], v[14:17], v[208:211], v[70:73]
	v_mfma_f32_16x16x32_bf16 v[70:73], v[180:183], v[196:199], v[98:101]
	v_mfma_f32_16x16x32_bf16 v[70:73], v[144:147], v[208:211], v[70:73]
	s_setprio 0
	s_barrier
;   #define LDA(dst,b,h) for(int m=0;m<4;++m)for(int k=0;k<2;++k) \
;     dst[m][k]=*reinterpret_cast<const bf16x8*>((char*)SA(b,h)+lds_byte(wr*64+m*16+fr,k*32+fq*8))
;   #define LDB(dst,b,h) for(int n=0;n<2;++n)for(int k=0;k<2;++k) \
;     dst[n][k]=*reinterpret_cast<const bf16x8*>((char*)SB(b,h)+lds_byte(wc*32+n*16+fr,k*32+fq*8))
;   #define MMA(ai,bj,At,Bt_) do{__builtin_amdgcn_s_setprio(1); \
;     for(int m=0;m<4;++m)for(int n=0;n<2;++n)for(int k=0;k<2;++k) \
;       acc[ai][bj][m][n]=__builtin_amdgcn_mfma_f32_16x16x32_bf16(Bt_[n][k],At[m][k],acc[ai][bj][m][n],0,0,0); \
;     __builtin_amdgcn_s_setprio(0);}while(0)
;   #define WAIT_V(n) asm volatile("s_waitcnt vmcnt(" #n ")":::"memory")
;   #define WAIT_L(n) asm volatile("s_waitcnt lgkmcnt(" #n ")":::"memory")
;   #define BAR __builtin_amdgcn_s_barrier()
; template <bool TWO, class MID> ...
;     ...
;   { LDB(B0,1,0); LDA(At,1,0); WAIT_V(2); BAR; WAIT_L(0); MMA(0,0,At,B0); BAR;
;     LDB(B1,1,1); WAIT_V(0); BAR; WAIT_L(0); MMA(0,1,At,B1); BAR;
;     LDA(At,1,1); BAR; WAIT_L(0); MMA(1,0,At,B0); MMA(1,1,At,B1); BAR; }
;   if(wr==0)BAR;
	ds_read_b128 v[130:133], v143
	ds_read_b128 v[148:151], v143 offset:1024
	ds_read_b128 v[204:207], v143 offset:2048
	ds_read_b128 v[220:223], v143 offset:3072
	s_waitcnt vmcnt(0)
	s_barrier
	s_waitcnt lgkmcnt(0)
	s_setprio 1
	v_mfma_f32_16x16x32_bf16 v[98:101], v[130:133], v[26:29], v[212:215]
	v_mfma_f32_16x16x32_bf16 v[26:29], v[204:207], v[26:29], v[90:93]
	v_mfma_f32_16x16x32_bf16 v[114:117], v[220:223], v[30:33], v[26:29]
	v_mfma_f32_16x16x32_bf16 v[26:29], v[130:133], v[42:45], v[168:171]
	v_mfma_f32_16x16x32_bf16 v[106:109], v[148:151], v[46:49], v[26:29]
	v_mfma_f32_16x16x32_bf16 v[26:29], v[204:207], v[42:45], v[82:85]
	v_mfma_f32_16x16x32_bf16 v[122:125], v[148:151], v[30:33], v[98:101]
	v_mfma_f32_16x16x32_bf16 v[98:101], v[220:223], v[46:49], v[26:29]
	v_mfma_f32_16x16x32_bf16 v[26:29], v[130:133], v[184:187], v[172:175]
	v_mfma_f32_16x16x32_bf16 v[90:93], v[148:151], v[188:191], v[26:29]
	v_mfma_f32_16x16x32_bf16 v[26:29], v[204:207], v[184:187], v[74:77]
	v_mfma_f32_16x16x32_bf16 v[82:85], v[220:223], v[188:191], v[26:29]
	v_mfma_f32_16x16x32_bf16 v[26:29], v[130:133], v[196:199], v[176:179]
	v_mfma_f32_16x16x32_bf16 v[74:77], v[148:151], v[208:211], v[26:29]
	v_mfma_f32_16x16x32_bf16 v[26:29], v[204:207], v[196:199], v[66:69]
	v_mfma_f32_16x16x32_bf16 v[66:69], v[220:223], v[208:211], v[26:29]
	s_setprio 0
	s_barrier
	ds_read_b128 v[168:171], v141 offset:49152
	ds_read_b128 v[140:143], v141 offset:50176
	ds_read_b128 v[172:175], v139 offset:49152
	ds_read_b128 v[176:179], v139 offset:50176
	ds_read_b128 v[184:187], v137 offset:49152
	ds_read_b128 v[136:139], v137 offset:50176
	ds_read_b128 v[188:191], v135 offset:49152
	ds_read_b128 v[196:199], v135 offset:50176
	s_barrier
	s_waitcnt lgkmcnt(0)
	s_setprio 1
	v_mfma_f32_16x16x32_bf16 v[26:29], v[10:13], v[168:171], v[62:65]
	v_mfma_f32_16x16x32_bf16 v[62:65], v[14:17], v[140:143], v[26:29]
	v_mfma_f32_16x16x32_bf16 v[26:29], v[180:183], v[168:171], v[58:61]
	v_mfma_f32_16x16x32_bf16 v[58:61], v[144:147], v[140:143], v[26:29]
	v_mfma_f32_16x16x32_bf16 v[26:29], v[10:13], v[172:175], v[54:57]
	v_mfma_f32_16x16x32_bf16 v[46:49], v[14:17], v[176:179], v[26:29]
	v_mfma_f32_16x16x32_bf16 v[26:29], v[180:183], v[172:175], v[50:53]
	v_mfma_f32_16x16x32_bf16 v[42:45], v[144:147], v[176:179], v[26:29]
	v_mfma_f32_16x16x32_bf16 v[26:29], v[10:13], v[184:187], v[200:203]
	v_mfma_f32_16x16x32_bf16 v[10:13], v[10:13], v[188:191], v[38:41]
	v_mfma_f32_16x16x32_bf16 v[30:33], v[14:17], v[136:139], v[26:29]
	v_mfma_f32_16x16x32_bf16 v[26:29], v[180:183], v[184:187], v[216:219]
	v_mfma_f32_16x16x32_bf16 v[14:17], v[14:17], v[196:199], v[10:13]
	v_mfma_f32_16x16x32_bf16 v[10:13], v[180:183], v[188:191], v[34:37]
	v_mfma_f32_16x16x32_bf16 v[26:29], v[144:147], v[136:139], v[26:29]
	v_mfma_f32_16x16x32_bf16 v[10:13], v[144:147], v[196:199], v[10:13]
	s_setprio 0
	s_setprio 1
	v_mfma_f32_16x16x32_bf16 v[34:37], v[130:133], v[168:171], v[152:155]
	v_mfma_f32_16x16x32_bf16 v[54:57], v[148:151], v[140:143], v[34:37]
	v_mfma_f32_16x16x32_bf16 v[34:37], v[204:207], v[168:171], v[156:159]
	v_mfma_f32_16x16x32_bf16 v[18:21], v[204:207], v[172:175], v[18:21]
	v_mfma_f32_16x16x32_bf16 v[50:53], v[220:223], v[140:143], v[34:37]
	v_mfma_f32_16x16x32_bf16 v[22:25], v[130:133], v[172:175], v[22:25]
	v_mfma_f32_16x16x32_bf16 v[34:37], v[220:223], v[176:179], v[18:21]
	v_mfma_f32_16x16x32_bf16 v[18:21], v[130:133], v[184:187], v[160:163]
	v_mfma_f32_16x16x32_bf16 v[38:41], v[148:151], v[176:179], v[22:25]
	v_mfma_f32_16x16x32_bf16 v[22:25], v[148:151], v[136:139], v[18:21]
	v_mfma_f32_16x16x32_bf16 v[18:21], v[204:207], v[184:187], v[164:167]
	v_mfma_f32_16x16x32_bf16 v[6:9], v[130:133], v[188:191], v[6:9]
	v_mfma_f32_16x16x32_bf16 v[2:5], v[204:207], v[188:191], v[2:5]
	v_mfma_f32_16x16x32_bf16 v[18:21], v[220:223], v[136:139], v[18:21]
	v_mfma_f32_16x16x32_bf16 v[6:9], v[148:151], v[196:199], v[6:9]
	v_mfma_f32_16x16x32_bf16 v[2:5], v[220:223], v[196:199], v[2:5]
	s_setprio 0
	v_cmp_gt_u32_e32 vcc, s30, v1
	s_barrier
	s_and_saveexec_b64 s[4:5], vcc
	s_cbranch_execz .LBB0_565
	s_barrier

;   #define LDA(dst,b,h) for(int m=0;m<4;++m)for(int k=0;k<2;++k) \
;     dst[m][k]=*reinterpret_cast<const bf16x8*>((char*)SA(b,h)+lds_byte(wr*64+m*16+fr,k*32+fq*8))
;   #define LDB(dst,b,h) for(int n=0;n<2;++n)for(int k=0;k<2;++k) \
;     dst[n][k]=*reinterpret_cast<const bf16x8*>((char*)SB(b,h)+lds_byte(wc*32+n*16+fr,k*32+fq*8))
;   #define MMA(ai,bj,At,Bt_) do{__builtin_amdgcn_s_setprio(1); \
;     for(int m=0;m<4;++m)for(int n=0;n<2;++n)for(int k=0;k<2;++k) \
;       acc[ai][bj][m][n]=__builtin_amdgcn_mfma_f32_16x16x32_bf16(Bt_[n][k],At[m][k],acc[ai][bj][m][n],0,0,0); \
;     __builtin_amdgcn_s_setprio(0);}while(0)
;   #define WAIT_V(n) asm volatile("s_waitcnt vmcnt(" #n ")":::"memory")
;   #define WAIT_L(n) asm volatile("s_waitcnt lgkmcnt(" #n ")":::"memory")
;   #define BAR __builtin_amdgcn_s_barrier()
;   #define SCHED __builtin_amdgcn_sched_barrier(0)
; __device__ __forceinline__ void gll16(const void* g, const void* l) {
;   const unsigned m = __builtin_amdgcn_readfirstlane((unsigned)(uintptr_t)l);
;   asm volatile("s_mov_b32 m0, %0\n\tglobal_load_lds_dwordx4 %1, off" :: "s"(m), "v"(g) : "memory");
; template <bool TWO, class MID> ...
;     ...
;     LDB(B0,0,0); SCHED; LDA(At,0,0); STAGE_A(SA(1,1),1,t+1);
;     WAIT_L(8); BAR; WAIT_L(0); MMA(0,0,At,B0); BAR; SCHED;
;     LDB(B1,0,1); STAGE_B(SB(0,0),0,t+2);
;     BAR; WAIT_L(0); MMA(0,1,At,B1); BAR;
;     LDA(At,0,1); STAGE_A(SA(0,0),0,t+2);
;     BAR; WAIT_L(0); MMA(1,0,At,B0); BAR; SCHED;
;     STAGE_B(SB(0,1),1,t+2);
;     WAIT_V(6); BAR; MMA(1,1,At,B1); BAR;
.LBB0_620:
	ds_read_b128 v[166:169], v149
	ds_read_b128 v[170:173], v149 offset:1024
	ds_read_b128 v[174:177], v149 offset:2048
	ds_read_b128 v[178:181], v149 offset:3072
	ds_read_b128 v[182:185], v141
	ds_read_b128 v[186:189], v141 offset:1024
	ds_read_b128 v[190:193], v139
	ds_read_b128 v[196:199], v139 offset:1024
	ds_read_b128 v[200:203], v137
	ds_read_b128 v[204:207], v137 offset:1024
	ds_read_b128 v[208:211], v135
	ds_read_b128 v[212:215], v135 offset:1024
	s_add_u32 s15, s0, s16
	s_addc_u32 s18, s1, s17
	s_add_u32 s24, s15, 0x10200080
	s_addc_u32 s25, s18, 0
	s_add_u32 m0, s98, 0xc000
	global_load_lds_dwordx4 v132, s[24:25]
	s_add_u32 m0, s98, 0xe000
	global_load_lds_dwordx4 v130, s[24:25]
	s_waitcnt lgkmcnt(8)
	s_barrier
	s_waitcnt lgkmcnt(0)
	s_setprio 1
	v_mfma_f32_16x16x32_bf16 v[126:129], v[166:169], v[182:185], v[126:129]
	v_mfma_f32_16x16x32_bf16 v[122:125], v[174:177], v[182:185], v[122:125]
	v_mfma_f32_16x16x32_bf16 v[118:121], v[166:169], v[190:193], v[118:121]
	v_mfma_f32_16x16x32_bf16 v[114:117], v[174:177], v[190:193], v[114:117]
	v_mfma_f32_16x16x32_bf16 v[110:113], v[166:169], v[200:203], v[110:113]
	v_mfma_f32_16x16x32_bf16 v[106:109], v[174:177], v[200:203], v[106:109]
	v_mfma_f32_16x16x32_bf16 v[102:105], v[166:169], v[208:211], v[102:105]
	v_mfma_f32_16x16x32_bf16 v[98:101], v[174:177], v[208:211], v[98:101]
	v_mfma_f32_16x16x32_bf16 v[126:129], v[170:173], v[186:189], v[126:129]
	v_mfma_f32_16x16x32_bf16 v[122:125], v[178:181], v[186:189], v[122:125]
	v_mfma_f32_16x16x32_bf16 v[118:121], v[170:173], v[196:199], v[118:121]
	v_mfma_f32_16x16x32_bf16 v[114:117], v[178:181], v[196:199], v[114:117]
	v_mfma_f32_16x16x32_bf16 v[110:113], v[170:173], v[204:207], v[110:113]
	v_mfma_f32_16x16x32_bf16 v[106:109], v[178:181], v[204:207], v[106:109]
	v_mfma_f32_16x16x32_bf16 v[102:105], v[170:173], v[212:215], v[102:105]
	v_mfma_f32_16x16x32_bf16 v[98:101], v[178:181], v[212:215], v[98:101]
	s_setprio 0
	s_barrier
	s_add_u32 s19, s0, s4
	ds_read_b128 v[216:219], v147
	ds_read_b128 v[220:223], v147 offset:1024
	ds_read_b128 v[224:227], v147 offset:2048
	ds_read_b128 v[228:231], v147 offset:3072
	s_addc_u32 s24, s1, s5
	s_add_u32 s26, s19, 0x5c00100
	s_addc_u32 s27, s24, 0
	s_add_u32 m0, s98, 0x10000
	global_load_lds_dwordx4 v132, s[26:27]
	s_add_u32 m0, s98, 0x12000
	global_load_lds_dwordx4 v130, s[26:27]
	s_barrier
	s_waitcnt lgkmcnt(0)
	s_setprio 1
	v_mfma_f32_16x16x32_bf16 v[94:97], v[216:219], v[182:185], v[94:97]
	v_mfma_f32_16x16x32_bf16 v[90:93], v[224:227], v[182:185], v[90:93]
	v_mfma_f32_16x16x32_bf16 v[86:89], v[216:219], v[190:193], v[86:89]
	v_mfma_f32_16x16x32_bf16 v[82:85], v[224:227], v[190:193], v[82:85]
	v_mfma_f32_16x16x32_bf16 v[78:81], v[216:219], v[200:203], v[78:81]
	v_mfma_f32_16x16x32_bf16 v[74:77], v[224:227], v[200:203], v[74:77]
	v_mfma_f32_16x16x32_bf16 v[70:73], v[216:219], v[208:211], v[70:73]
	v_mfma_f32_16x16x32_bf16 v[66:69], v[224:227], v[208:211], v[66:69]
	v_mfma_f32_16x16x32_bf16 v[94:97], v[220:223], v[186:189], v[94:97]
	v_mfma_f32_16x16x32_bf16 v[90:93], v[228:231], v[186:189], v[90:93]
	v_mfma_f32_16x16x32_bf16 v[86:89], v[220:223], v[196:199], v[86:89]
	v_mfma_f32_16x16x32_bf16 v[82:85], v[228:231], v[196:199], v[82:85]
	v_mfma_f32_16x16x32_bf16 v[78:81], v[220:223], v[204:207], v[78:81]
	v_mfma_f32_16x16x32_bf16 v[74:77], v[228:231], v[204:207], v[74:77]
	v_mfma_f32_16x16x32_bf16 v[70:73], v[220:223], v[212:215], v[70:73]
	v_mfma_f32_16x16x32_bf16 v[66:69], v[228:231], v[212:215], v[66:69]
	s_setprio 0
	s_barrier
	ds_read_b128 v[182:185], v141 offset:16384
	ds_read_b128 v[186:189], v141 offset:17408
	ds_read_b128 v[190:193], v139 offset:16384
	ds_read_b128 v[196:199], v139 offset:17408
	ds_read_b128 v[200:203], v137 offset:16384
	ds_read_b128 v[204:207], v137 offset:17408
	ds_read_b128 v[208:211], v135 offset:16384
	ds_read_b128 v[212:215], v135 offset:17408
	s_add_u32 s26, s15, 0x10000100
	s_addc_u32 s27, s18, 0
	s_add_u32 m0, s98, 0x0
	global_load_lds_dwordx4 v132, s[26:27]
	s_add_u32 m0, s98, 0x2000
	global_load_lds_dwordx4 v130, s[26:27]
	s_barrier
	s_waitcnt lgkmcnt(0)
	s_setprio 1
	v_mfma_f32_16x16x32_bf16 v[62:65], v[166:169], v[182:185], v[62:65]
	v_mfma_f32_16x16x32_bf16 v[58:61], v[174:177], v[182:185], v[58:61]
	v_mfma_f32_16x16x32_bf16 v[54:57], v[166:169], v[190:193], v[54:57]
	v_mfma_f32_16x16x32_bf16 v[50:53], v[174:177], v[190:193], v[50:53]
	v_mfma_f32_16x16x32_bf16 v[46:49], v[166:169], v[200:203], v[46:49]
	v_mfma_f32_16x16x32_bf16 v[42:45], v[174:177], v[200:203], v[42:45]
	v_mfma_f32_16x16x32_bf16 v[38:41], v[166:169], v[208:211], v[38:41]
	v_mfma_f32_16x16x32_bf16 v[34:37], v[174:177], v[208:211], v[34:37]
	v_mfma_f32_16x16x32_bf16 v[62:65], v[170:173], v[186:189], v[62:65]
	v_mfma_f32_16x16x32_bf16 v[58:61], v[178:181], v[186:189], v[58:61]
	v_mfma_f32_16x16x32_bf16 v[54:57], v[170:173], v[196:199], v[54:57]
	v_mfma_f32_16x16x32_bf16 v[50:53], v[178:181], v[196:199], v[50:53]
	v_mfma_f32_16x16x32_bf16 v[46:49], v[170:173], v[204:207], v[46:49]
	v_mfma_f32_16x16x32_bf16 v[42:45], v[178:181], v[204:207], v[42:45]
	v_mfma_f32_16x16x32_bf16 v[38:41], v[170:173], v[212:215], v[38:41]
	v_mfma_f32_16x16x32_bf16 v[34:37], v[178:181], v[212:215], v[34:37]
	s_setprio 0
	s_barrier
	s_add_u32 s26, s19, 0x5e00100
	s_addc_u32 s27, s24, 0
	s_add_u32 m0, s98, 0x14000
	global_load_lds_dwordx4 v132, s[26:27]
	s_add_u32 m0, s98, 0x16000
	global_load_lds_dwordx4 v130, s[26:27]
	s_waitcnt vmcnt(6)
	s_barrier
;   #define LDA(dst,b,h) for(int m=0;m<4;++m)for(int k=0;k<2;++k) \
;     dst[m][k]=*reinterpret_cast<const bf16x8*>((char*)SA(b,h)+lds_byte(wr*64+m*16+fr,k*32+fq*8))
;   #define LDB(dst,b,h) for(int n=0;n<2;++n)for(int k=0;k<2;++k) \
;     dst[n][k]=*reinterpret_cast<const bf16x8*>((char*)SB(b,h)+lds_byte(wc*32+n*16+fr,k*32+fq*8))
;   #define MMA(ai,bj,At,Bt_) do{__builtin_amdgcn_s_setprio(1); \
;     for(int m=0;m<4;++m)for(int n=0;n<2;++n)for(int k=0;k<2;++k) \
;       acc[ai][bj][m][n]=__builtin_amdgcn_mfma_f32_16x16x32_bf16(Bt_[n][k],At[m][k],acc[ai][bj][m][n],0,0,0); \
;     __builtin_amdgcn_s_setprio(0);}while(0)
;   #define WAIT_V(n) asm volatile("s_waitcnt vmcnt(" #n ")":::"memory")
;   #define WAIT_L(n) asm volatile("s_waitcnt lgkmcnt(" #n ")":::"memory")
;   #define BAR __builtin_amdgcn_s_barrier()
;   #define SCHED __builtin_amdgcn_sched_barrier(0)
; template <bool TWO, class MID> ...
;     ...
;     WAIT_V(6); BAR; MMA(1,1,At,B1); BAR;
;     LDB(B0,1,0); SCHED; LDA(At,1,0); STAGE_A(SA(0,1),1,t+2);
;     WAIT_L(8); BAR; WAIT_L(0); MMA(0,0,At,B0); BAR; SCHED;
;     LDB(B1,1,1); STAGE_B(SB(1,0),0,t+3);
;     BAR; WAIT_L(0); MMA(0,1,At,B1); BAR;
;     LDA(At,1,1); STAGE_A(SA(1,0),0,t+3);
;     BAR; WAIT_L(0); MMA(1,0,At,B0); BAR; SCHED;
;     STAGE_B(SB(1,1),1,t+3);
	s_setprio 1
	v_mfma_f32_16x16x32_bf16 v[30:33], v[216:219], v[182:185], v[30:33]
	v_mfma_f32_16x16x32_bf16 v[26:29], v[224:227], v[182:185], v[26:29]
	v_mfma_f32_16x16x32_bf16 v[22:25], v[216:219], v[190:193], v[22:25]
	v_mfma_f32_16x16x32_bf16 v[18:21], v[224:227], v[190:193], v[18:21]
	v_mfma_f32_16x16x32_bf16 v[14:17], v[216:219], v[200:203], v[14:17]
	v_mfma_f32_16x16x32_bf16 v[10:13], v[224:227], v[200:203], v[10:13]
	v_mfma_f32_16x16x32_bf16 v[6:9], v[216:219], v[208:211], v[6:9]
	v_mfma_f32_16x16x32_bf16 v[2:5], v[224:227], v[208:211], v[2:5]
	v_mfma_f32_16x16x32_bf16 v[30:33], v[220:223], v[186:189], v[30:33]
	v_mfma_f32_16x16x32_bf16 v[26:29], v[228:231], v[186:189], v[26:29]
	v_mfma_f32_16x16x32_bf16 v[22:25], v[220:223], v[196:199], v[22:25]
	v_mfma_f32_16x16x32_bf16 v[18:21], v[228:231], v[196:199], v[18:21]
	v_mfma_f32_16x16x32_bf16 v[14:17], v[220:223], v[204:207], v[14:17]
	v_mfma_f32_16x16x32_bf16 v[10:13], v[228:231], v[204:207], v[10:13]
	v_mfma_f32_16x16x32_bf16 v[6:9], v[220:223], v[212:215], v[6:9]
	v_mfma_f32_16x16x32_bf16 v[2:5], v[228:231], v[212:215], v[2:5]
	s_setprio 0
	s_barrier
	ds_read_b128 v[166:169], v145
	ds_read_b128 v[170:173], v145 offset:1024
	ds_read_b128 v[174:177], v145 offset:2048
	ds_read_b128 v[178:181], v145 offset:3072
	ds_read_b128 v[182:185], v141 offset:32768
	ds_read_b128 v[186:189], v141 offset:33792
	ds_read_b128 v[190:193], v139 offset:32768
	ds_read_b128 v[196:199], v139 offset:33792
	ds_read_b128 v[200:203], v137 offset:32768
	ds_read_b128 v[204:207], v137 offset:33792
	ds_read_b128 v[208:211], v135 offset:32768
	ds_read_b128 v[212:215], v135 offset:33792
	s_add_u32 s26, s15, 0x10200100
	s_addc_u32 s27, s18, 0
	s_add_u32 m0, s98, 0x4000
	global_load_lds_dwordx4 v132, s[26:27]
	s_add_u32 m0, s98, 0x6000
	global_load_lds_dwordx4 v130, s[26:27]
	s_waitcnt lgkmcnt(8)
	s_barrier
	s_waitcnt lgkmcnt(0)
	s_setprio 1
	v_mfma_f32_16x16x32_bf16 v[126:129], v[166:169], v[182:185], v[126:129]
	v_mfma_f32_16x16x32_bf16 v[122:125], v[174:177], v[182:185], v[122:125]
	v_mfma_f32_16x16x32_bf16 v[118:121], v[166:169], v[190:193], v[118:121]
	v_mfma_f32_16x16x32_bf16 v[114:117], v[174:177], v[190:193], v[114:117]
	v_mfma_f32_16x16x32_bf16 v[110:113], v[166:169], v[200:203], v[110:113]
	v_mfma_f32_16x16x32_bf16 v[106:109], v[174:177], v[200:203], v[106:109]
	v_mfma_f32_16x16x32_bf16 v[102:105], v[166:169], v[208:211], v[102:105]
	v_mfma_f32_16x16x32_bf16 v[98:101], v[174:177], v[208:211], v[98:101]
	v_mfma_f32_16x16x32_bf16 v[126:129], v[170:173], v[186:189], v[126:129]
	v_mfma_f32_16x16x32_bf16 v[122:125], v[178:181], v[186:189], v[122:125]
	v_mfma_f32_16x16x32_bf16 v[118:121], v[170:173], v[196:199], v[118:121]
	v_mfma_f32_16x16x32_bf16 v[114:117], v[178:181], v[196:199], v[114:117]
	v_mfma_f32_16x16x32_bf16 v[110:113], v[170:173], v[204:207], v[110:113]
	v_mfma_f32_16x16x32_bf16 v[106:109], v[178:181], v[204:207], v[106:109]
	v_mfma_f32_16x16x32_bf16 v[102:105], v[170:173], v[212:215], v[102:105]
	v_mfma_f32_16x16x32_bf16 v[98:101], v[178:181], v[212:215], v[98:101]
	s_setprio 0
	s_barrier
	ds_read_b128 v[216:219], v143
	ds_read_b128 v[220:223], v143 offset:1024
	ds_read_b128 v[224:227], v143 offset:2048
	ds_read_b128 v[228:231], v143 offset:3072
	s_add_u32 s26, s19, 0x5c00180
	s_addc_u32 s27, s24, 0
	s_add_u32 m0, s98, 0x18000
	global_load_lds_dwordx4 v132, s[26:27]
	s_add_u32 m0, s98, 0x1a000
	global_load_lds_dwordx4 v130, s[26:27]
	s_barrier
	s_waitcnt lgkmcnt(0)
	s_setprio 1
	v_mfma_f32_16x16x32_bf16 v[94:97], v[216:219], v[182:185], v[94:97]
	v_mfma_f32_16x16x32_bf16 v[90:93], v[224:227], v[182:185], v[90:93]
	v_mfma_f32_16x16x32_bf16 v[86:89], v[216:219], v[190:193], v[86:89]
	v_mfma_f32_16x16x32_bf16 v[82:85], v[224:227], v[190:193], v[82:85]
	v_mfma_f32_16x16x32_bf16 v[78:81], v[216:219], v[200:203], v[78:81]
	v_mfma_f32_16x16x32_bf16 v[74:77], v[224:227], v[200:203], v[74:77]
	v_mfma_f32_16x16x32_bf16 v[70:73], v[216:219], v[208:211], v[70:73]
	v_mfma_f32_16x16x32_bf16 v[66:69], v[224:227], v[208:211], v[66:69]
	v_mfma_f32_16x16x32_bf16 v[94:97], v[220:223], v[186:189], v[94:97]
	v_mfma_f32_16x16x32_bf16 v[90:93], v[228:231], v[186:189], v[90:93]
	v_mfma_f32_16x16x32_bf16 v[86:89], v[220:223], v[196:199], v[86:89]
	v_mfma_f32_16x16x32_bf16 v[82:85], v[228:231], v[196:199], v[82:85]
	v_mfma_f32_16x16x32_bf16 v[78:81], v[220:223], v[204:207], v[78:81]
	v_mfma_f32_16x16x32_bf16 v[74:77], v[228:231], v[204:207], v[74:77]
	v_mfma_f32_16x16x32_bf16 v[70:73], v[220:223], v[212:215], v[70:73]
	v_mfma_f32_16x16x32_bf16 v[66:69], v[228:231], v[212:215], v[66:69]
	s_setprio 0
	s_barrier
	ds_read_b128 v[182:185], v141 offset:49152
	ds_read_b128 v[186:189], v141 offset:50176
	ds_read_b128 v[190:193], v139 offset:49152
	ds_read_b128 v[196:199], v139 offset:50176
	ds_read_b128 v[200:203], v137 offset:49152
	ds_read_b128 v[204:207], v137 offset:50176
	ds_read_b128 v[208:211], v135 offset:49152
	ds_read_b128 v[212:215], v135 offset:50176
	s_add_u32 s26, s15, 0x10000180
	s_addc_u32 s27, s18, 0
	s_add_u32 m0, s98, 0x8000
	global_load_lds_dwordx4 v132, s[26:27]
	s_add_u32 m0, s98, 0xa000
	global_load_lds_dwordx4 v130, s[26:27]
	s_barrier
;   #define LDA(dst,b,h) for(int m=0;m<4;++m)for(int k=0;k<2;++k) \
;     dst[m][k]=*reinterpret_cast<const bf16x8*>((char*)SA(b,h)+lds_byte(wr*64+m*16+fr,k*32+fq*8))
;   #define LDB(dst,b,h) for(int n=0;n<2;++n)for(int k=0;k<2;++k) \
;     dst[n][k]=*reinterpret_cast<const bf16x8*>((char*)SB(b,h)+lds_byte(wc*32+n*16+fr,k*32+fq*8))
;   #define MMA(ai,bj,At,Bt_) do{__builtin_amdgcn_s_setprio(1); \
;     for(int m=0;m<4;++m)for(int n=0;n<2;++n)for(int k=0;k<2;++k) \
;       acc[ai][bj][m][n]=__builtin_amdgcn_mfma_f32_16x16x32_bf16(Bt_[n][k],At[m][k],acc[ai][bj][m][n],0,0,0); \
;     __builtin_amdgcn_s_setprio(0);}while(0)
;   #define WAIT_V(n) asm volatile("s_waitcnt vmcnt(" #n ")":::"memory")
;   #define WAIT_L(n) asm volatile("s_waitcnt lgkmcnt(" #n ")":::"memory")
;   #define BAR __builtin_amdgcn_s_barrier()
; template <bool TWO, class MID> ...
;     ...
;     STAGE_B(SB(1,1),1,t+3);
;     WAIT_V(6); BAR; MMA(1,1,At,B1); BAR;
;   }
;   { LDB(B0,0,0); LDA(At,0,0); STAGE_A(SA(1,1),1,nt-1);
;     BAR; WAIT_L(0); MMA(0,0,At,B0); BAR;
;     LDB(B1,0,1); BAR; WAIT_L(0); MMA(0,1,At,B1); BAR;
;     LDA(At,0,1); WAIT_V(4); BAR; WAIT_L(0); MMA(1,0,At,B0); MMA(1,1,At,B1); BAR; }
	s_waitcnt lgkmcnt(0)
	s_setprio 1
	v_mfma_f32_16x16x32_bf16 v[62:65], v[166:169], v[182:185], v[62:65]
	v_mfma_f32_16x16x32_bf16 v[58:61], v[174:177], v[182:185], v[58:61]
	v_mfma_f32_16x16x32_bf16 v[54:57], v[166:169], v[190:193], v[54:57]
	v_mfma_f32_16x16x32_bf16 v[50:53], v[174:177], v[190:193], v[50:53]
	v_mfma_f32_16x16x32_bf16 v[46:49], v[166:169], v[200:203], v[46:49]
	v_mfma_f32_16x16x32_bf16 v[42:45], v[174:177], v[200:203], v[42:45]
	v_mfma_f32_16x16x32_bf16 v[38:41], v[166:169], v[208:211], v[38:41]
	v_mfma_f32_16x16x32_bf16 v[34:37], v[174:177], v[208:211], v[34:37]
	v_mfma_f32_16x16x32_bf16 v[62:65], v[170:173], v[186:189], v[62:65]
	v_mfma_f32_16x16x32_bf16 v[58:61], v[178:181], v[186:189], v[58:61]
	v_mfma_f32_16x16x32_bf16 v[54:57], v[170:173], v[196:199], v[54:57]
	v_mfma_f32_16x16x32_bf16 v[50:53], v[178:181], v[196:199], v[50:53]
	v_mfma_f32_16x16x32_bf16 v[46:49], v[170:173], v[204:207], v[46:49]
	v_mfma_f32_16x16x32_bf16 v[42:45], v[178:181], v[204:207], v[42:45]
	v_mfma_f32_16x16x32_bf16 v[38:41], v[170:173], v[212:215], v[38:41]
	v_mfma_f32_16x16x32_bf16 v[34:37], v[178:181], v[212:215], v[34:37]
	s_setprio 0
	s_barrier
	s_add_u32 s18, s19, 0x5e00180
	s_addc_u32 s19, s24, 0
	s_add_u32 m0, s98, 0x1c000
	global_load_lds_dwordx4 v132, s[18:19]
	s_add_u32 m0, s98, 0x1e000
	global_load_lds_dwordx4 v130, s[18:19]
	s_waitcnt vmcnt(6)
	s_barrier
	s_setprio 1
	v_mfma_f32_16x16x32_bf16 v[30:33], v[216:219], v[182:185], v[30:33]
	v_mfma_f32_16x16x32_bf16 v[26:29], v[224:227], v[182:185], v[26:29]
	v_mfma_f32_16x16x32_bf16 v[22:25], v[216:219], v[190:193], v[22:25]
	v_mfma_f32_16x16x32_bf16 v[18:21], v[224:227], v[190:193], v[18:21]
	v_mfma_f32_16x16x32_bf16 v[14:17], v[216:219], v[200:203], v[14:17]
	v_mfma_f32_16x16x32_bf16 v[10:13], v[224:227], v[200:203], v[10:13]
	v_mfma_f32_16x16x32_bf16 v[6:9], v[216:219], v[208:211], v[6:9]
	v_mfma_f32_16x16x32_bf16 v[2:5], v[224:227], v[208:211], v[2:5]
	v_mfma_f32_16x16x32_bf16 v[30:33], v[220:223], v[186:189], v[30:33]
	v_mfma_f32_16x16x32_bf16 v[26:29], v[228:231], v[186:189], v[26:29]
	v_mfma_f32_16x16x32_bf16 v[22:25], v[220:223], v[196:199], v[22:25]
	v_mfma_f32_16x16x32_bf16 v[18:21], v[228:231], v[196:199], v[18:21]
	v_mfma_f32_16x16x32_bf16 v[14:17], v[220:223], v[204:207], v[14:17]
	v_mfma_f32_16x16x32_bf16 v[10:13], v[228:231], v[204:207], v[10:13]
	v_mfma_f32_16x16x32_bf16 v[6:9], v[220:223], v[212:215], v[6:9]
	v_mfma_f32_16x16x32_bf16 v[2:5], v[228:231], v[212:215], v[2:5]
	s_setprio 0
	s_add_i32 s14, s14, 2
	s_add_u32 s0, s0, 0x100
	s_addc_u32 s1, s1, 0
	s_cmpk_lt_u32 s14, 0x7c
	s_barrier
	s_cbranch_scc1 .LBB0_620
	ds_read_b128 v[152:155], v149
	ds_read_b128 v[156:159], v149 offset:1024
	ds_read_b128 v[160:163], v149 offset:2048
	ds_read_b128 v[164:167], v149 offset:3072
	ds_read_b128 v[168:171], v141
	ds_read_b128 v[172:175], v141 offset:1024
	ds_read_b128 v[176:179], v139
	ds_read_b128 v[180:183], v139 offset:1024
	ds_read_b128 v[184:187], v137
	ds_read_b128 v[188:191], v137 offset:1024
	ds_read_b128 v[196:199], v135
	ds_read_b128 v[200:203], v135 offset:1024
	s_add_u32 s0, s12, 0x203f80
	s_addc_u32 s1, s13, 0
	v_lshl_add_u64 v[132:133], s[0:1], 0, v[132:133]
	v_readfirstlane_b32 s12, v148
	s_mov_b32 m0, s12
	global_load_lds_dwordx4 v[132:133], off
	v_lshl_add_u64 v[130:131], s[0:1], 0, v[130:131]
	v_readfirstlane_b32 s0, v150
	s_mov_b32 m0, s0
	global_load_lds_dwordx4 v[130:131], off
	s_barrier
	s_waitcnt lgkmcnt(0)
	s_setprio 1
	v_mfma_f32_16x16x32_bf16 v[126:129], v[152:155], v[168:171], v[126:129]
	v_mfma_f32_16x16x32_bf16 v[122:125], v[160:163], v[168:171], v[122:125]
	v_mfma_f32_16x16x32_bf16 v[118:121], v[152:155], v[176:179], v[118:121]
	v_mfma_f32_16x16x32_bf16 v[114:117], v[160:163], v[176:179], v[114:117]
	v_mfma_f32_16x16x32_bf16 v[102:105], v[152:155], v[196:199], v[102:105]
	v_mfma_f32_16x16x32_bf16 v[98:101], v[160:163], v[196:199], v[98:101]
	v_mfma_f32_16x16x32_bf16 v[126:129], v[156:159], v[172:175], v[126:129]
	v_mfma_f32_16x16x32_bf16 v[122:125], v[164:167], v[172:175], v[122:125]
	v_mfma_f32_16x16x32_bf16 v[118:121], v[156:159], v[180:183], v[118:121]
	v_mfma_f32_16x16x32_bf16 v[114:117], v[164:167], v[180:183], v[114:117]
	v_mfma_f32_16x16x32_bf16 v[110:113], v[152:155], v[184:187], v[110:113]
	v_mfma_f32_16x16x32_bf16 v[106:109], v[160:163], v[184:187], v[106:109]
	v_mfma_f32_16x16x32_bf16 v[102:105], v[156:159], v[200:203], v[102:105]
	v_mfma_f32_16x16x32_bf16 v[98:101], v[164:167], v[200:203], v[98:101]
	v_mfma_f32_16x16x32_bf16 v[130:133], v[156:159], v[188:191], v[110:113]
	v_mfma_f32_16x16x32_bf16 v[148:151], v[164:167], v[188:191], v[106:109]
	s_setprio 0
	s_barrier
	s_nop 0
	ds_read_b128 v[106:109], v147
	ds_read_b128 v[110:113], v147 offset:1024
	ds_read_b128 v[204:207], v147 offset:2048
	ds_read_b128 v[208:211], v147 offset:3072
	s_barrier
	s_waitcnt lgkmcnt(0)
	s_setprio 1
	v_mfma_f32_16x16x32_bf16 v[86:89], v[106:109], v[176:179], v[86:89]
	v_mfma_f32_16x16x32_bf16 v[82:85], v[204:207], v[176:179], v[82:85]
	v_mfma_f32_16x16x32_bf16 v[70:73], v[106:109], v[196:199], v[70:73]
	v_mfma_f32_16x16x32_bf16 v[66:69], v[204:207], v[196:199], v[66:69]
	v_mfma_f32_16x16x32_bf16 v[94:97], v[106:109], v[168:171], v[94:97]
	v_mfma_f32_16x16x32_bf16 v[90:93], v[204:207], v[168:171], v[90:93]
	v_mfma_f32_16x16x32_bf16 v[86:89], v[110:113], v[180:183], v[86:89]
	v_mfma_f32_16x16x32_bf16 v[82:85], v[208:211], v[180:183], v[82:85]
	v_mfma_f32_16x16x32_bf16 v[78:81], v[106:109], v[184:187], v[78:81]
	v_mfma_f32_16x16x32_bf16 v[74:77], v[204:207], v[184:187], v[74:77]
	v_mfma_f32_16x16x32_bf16 v[70:73], v[110:113], v[200:203], v[70:73]
	v_mfma_f32_16x16x32_bf16 v[66:69], v[208:211], v[200:203], v[66:69]
	v_mfma_f32_16x16x32_bf16 v[212:215], v[110:113], v[172:175], v[94:97]
	v_mfma_f32_16x16x32_bf16 v[168:171], v[208:211], v[172:175], v[90:93]
	v_mfma_f32_16x16x32_bf16 v[172:175], v[110:113], v[188:191], v[78:81]
	v_mfma_f32_16x16x32_bf16 v[176:179], v[208:211], v[188:191], v[74:77]
	s_setprio 0
	s_barrier
;   #define LDA(dst,b,h) for(int m=0;m<4;++m)for(int k=0;k<2;++k) \
;     dst[m][k]=*reinterpret_cast<const bf16x8*>((char*)SA(b,h)+lds_byte(wr*64+m*16+fr,k*32+fq*8))
;   #define LDB(dst,b,h) for(int n=0;n<2;++n)for(int k=0;k<2;++k) \
;     dst[n][k]=*reinterpret_cast<const bf16x8*>((char*)SB(b,h)+lds_byte(wc*32+n*16+fr,k*32+fq*8))
;   #define MMA(ai,bj,At,Bt_) do{__builtin_amdgcn_s_setprio(1); \
;     for(int m=0;m<4;++m)for(int n=0;n<2;++n)for(int k=0;k<2;++k) \
;       acc[ai][bj][m][n]=__builtin_amdgcn_mfma_f32_16x16x32_bf16(Bt_[n][k],At[m][k],acc[ai][bj][m][n],0,0,0); \
;     __builtin_amdgcn_s_setprio(0);}while(0)
;   #define WAIT_V(n) asm volatile("s_waitcnt vmcnt(" #n ")":::"memory")
;   #define WAIT_L(n) asm volatile("s_waitcnt lgkmcnt(" #n ")":::"memory")
;   #define BAR __builtin_amdgcn_s_barrier()
; template <bool TWO, class MID> ...
;     ...
;     LDA(At,0,1); WAIT_V(4); BAR; WAIT_L(0); MMA(1,0,At,B0); MMA(1,1,At,B1); BAR; }
;   { LDB(B0,1,0); LDA(At,1,0); WAIT_V(2); BAR; WAIT_L(0); MMA(0,0,At,B0); BAR;
	s_nop 0
	ds_read_b128 v[74:77], v141 offset:16384
	ds_read_b128 v[78:81], v141 offset:17408
	ds_read_b128 v[90:93], v139 offset:16384
	ds_read_b128 v[94:97], v139 offset:17408
	ds_read_b128 v[180:183], v137 offset:16384
	ds_read_b128 v[184:187], v137 offset:17408
	ds_read_b128 v[188:191], v135 offset:16384
	ds_read_b128 v[196:199], v135 offset:17408
	s_waitcnt vmcnt(4)
	s_barrier
	s_waitcnt lgkmcnt(0)
	s_setprio 1
	v_mfma_f32_16x16x32_bf16 v[62:65], v[152:155], v[74:77], v[62:65]
	v_mfma_f32_16x16x32_bf16 v[58:61], v[160:163], v[74:77], v[58:61]
	v_mfma_f32_16x16x32_bf16 v[54:57], v[152:155], v[90:93], v[54:57]
	v_mfma_f32_16x16x32_bf16 v[50:53], v[160:163], v[90:93], v[50:53]
	v_mfma_f32_16x16x32_bf16 v[38:41], v[152:155], v[188:191], v[38:41]
	v_mfma_f32_16x16x32_bf16 v[34:37], v[160:163], v[188:191], v[34:37]
	v_mfma_f32_16x16x32_bf16 v[62:65], v[156:159], v[78:81], v[62:65]
	v_mfma_f32_16x16x32_bf16 v[58:61], v[164:167], v[78:81], v[58:61]
	v_mfma_f32_16x16x32_bf16 v[54:57], v[156:159], v[94:97], v[54:57]
	v_mfma_f32_16x16x32_bf16 v[50:53], v[164:167], v[94:97], v[50:53]
	v_mfma_f32_16x16x32_bf16 v[46:49], v[152:155], v[180:183], v[46:49]
	v_mfma_f32_16x16x32_bf16 v[42:45], v[160:163], v[180:183], v[42:45]
	v_mfma_f32_16x16x32_bf16 v[38:41], v[156:159], v[196:199], v[38:41]
	v_mfma_f32_16x16x32_bf16 v[34:37], v[164:167], v[196:199], v[34:37]
	v_mfma_f32_16x16x32_bf16 v[200:203], v[156:159], v[184:187], v[46:49]
	v_mfma_f32_16x16x32_bf16 v[216:219], v[164:167], v[184:187], v[42:45]
	s_setprio 0
	s_setprio 1
	v_mfma_f32_16x16x32_bf16 v[22:25], v[106:109], v[90:93], v[22:25]
	v_mfma_f32_16x16x32_bf16 v[18:21], v[204:207], v[90:93], v[18:21]
	v_mfma_f32_16x16x32_bf16 v[6:9], v[106:109], v[188:191], v[6:9]
	v_mfma_f32_16x16x32_bf16 v[2:5], v[204:207], v[188:191], v[2:5]
	v_mfma_f32_16x16x32_bf16 v[30:33], v[106:109], v[74:77], v[30:33]
	v_mfma_f32_16x16x32_bf16 v[26:29], v[204:207], v[74:77], v[26:29]
	v_mfma_f32_16x16x32_bf16 v[22:25], v[110:113], v[94:97], v[22:25]
	v_mfma_f32_16x16x32_bf16 v[18:21], v[208:211], v[94:97], v[18:21]
	v_mfma_f32_16x16x32_bf16 v[14:17], v[106:109], v[180:183], v[14:17]
	v_mfma_f32_16x16x32_bf16 v[10:13], v[204:207], v[180:183], v[10:13]
	v_mfma_f32_16x16x32_bf16 v[6:9], v[110:113], v[196:199], v[6:9]
	v_mfma_f32_16x16x32_bf16 v[2:5], v[208:211], v[196:199], v[2:5]
	v_mfma_f32_16x16x32_bf16 v[152:155], v[110:113], v[78:81], v[30:33]
	v_mfma_f32_16x16x32_bf16 v[156:159], v[208:211], v[78:81], v[26:29]
	v_mfma_f32_16x16x32_bf16 v[160:163], v[110:113], v[184:187], v[14:17]
	v_mfma_f32_16x16x32_bf16 v[164:167], v[208:211], v[184:187], v[10:13]
	s_setprio 0
	s_barrier
	s_nop 0
	ds_read_b128 v[10:13], v145
	ds_read_b128 v[14:17], v145 offset:1024
	ds_read_b128 v[180:183], v145 offset:2048
	ds_read_b128 v[144:147], v145 offset:3072
	ds_read_b128 v[26:29], v141 offset:32768
	ds_read_b128 v[30:33], v141 offset:33792
	ds_read_b128 v[42:45], v139 offset:32768
	ds_read_b128 v[46:49], v139 offset:33792
	ds_read_b128 v[184:187], v137 offset:32768
	ds_read_b128 v[188:191], v137 offset:33792
	ds_read_b128 v[196:199], v135 offset:32768
	ds_read_b128 v[204:207], v135 offset:33792
	s_waitcnt vmcnt(2)
	s_barrier
	s_waitcnt lgkmcnt(0)
	s_setprio 1
	v_mfma_f32_16x16x32_bf16 v[74:77], v[10:13], v[26:29], v[126:129]
	v_mfma_f32_16x16x32_bf16 v[126:129], v[14:17], v[30:33], v[74:77]
	v_mfma_f32_16x16x32_bf16 v[74:77], v[180:183], v[26:29], v[122:125]
	v_mfma_f32_16x16x32_bf16 v[122:125], v[144:147], v[30:33], v[74:77]
	v_mfma_f32_16x16x32_bf16 v[74:77], v[10:13], v[42:45], v[118:121]
	v_mfma_f32_16x16x32_bf16 v[110:113], v[14:17], v[46:49], v[74:77]
	v_mfma_f32_16x16x32_bf16 v[74:77], v[180:183], v[42:45], v[114:117]
	v_mfma_f32_16x16x32_bf16 v[106:109], v[144:147], v[46:49], v[74:77]
	v_mfma_f32_16x16x32_bf16 v[74:77], v[10:13], v[184:187], v[130:133]
	v_mfma_f32_16x16x32_bf16 v[94:97], v[14:17], v[188:191], v[74:77]
	v_mfma_f32_16x16x32_bf16 v[74:77], v[180:183], v[184:187], v[148:151]
	v_mfma_f32_16x16x32_bf16 v[90:93], v[144:147], v[188:191], v[74:77]
	v_mfma_f32_16x16x32_bf16 v[74:77], v[10:13], v[196:199], v[102:105]
	v_mfma_f32_16x16x32_bf16 v[78:81], v[14:17], v[204:207], v[74:77]
	v_mfma_f32_16x16x32_bf16 v[74:77], v[180:183], v[196:199], v[98:101]
	v_mfma_f32_16x16x32_bf16 v[74:77], v[144:147], v[204:207], v[74:77]
	s_setprio 0
	s_barrier
;   #define LDA(dst,b,h) for(int m=0;m<4;++m)for(int k=0;k<2;++k) \
;     dst[m][k]=*reinterpret_cast<const bf16x8*>((char*)SA(b,h)+lds_byte(wr*64+m*16+fr,k*32+fq*8))
;   #define LDB(dst,b,h) for(int n=0;n<2;++n)for(int k=0;k<2;++k) \
;     dst[n][k]=*reinterpret_cast<const bf16x8*>((char*)SB(b,h)+lds_byte(wc*32+n*16+fr,k*32+fq*8))
;   #define MMA(ai,bj,At,Bt_) do{__builtin_amdgcn_s_setprio(1); \
;     for(int m=0;m<4;++m)for(int n=0;n<2;++n)for(int k=0;k<2;++k) \
;       acc[ai][bj][m][n]=__builtin_amdgcn_mfma_f32_16x16x32_bf16(Bt_[n][k],At[m][k],acc[ai][bj][m][n],0,0,0); \
;     __builtin_amdgcn_s_setprio(0);}while(0)
;   #define WAIT_V(n) asm volatile("s_waitcnt vmcnt(" #n ")":::"memory")
;   #define WAIT_L(n) asm volatile("s_waitcnt lgkmcnt(" #n ")":::"memory")
;   #define BAR __builtin_amdgcn_s_barrier()
; template <bool TWO, class MID> ...
;     ...
;   { LDB(B0,1,0); LDA(At,1,0); WAIT_V(2); BAR; WAIT_L(0); MMA(0,0,At,B0); BAR;
;     LDB(B1,1,1); WAIT_V(0); BAR; WAIT_L(0); MMA(0,1,At,B1); BAR;
;     LDA(At,1,1); BAR; WAIT_L(0); MMA(1,0,At,B0); MMA(1,1,At,B1); BAR; }
;   if(wr==0)BAR;
	ds_read_b128 v[130:133], v143
	ds_read_b128 v[148:151], v143 offset:1024
	ds_read_b128 v[208:211], v143 offset:2048
	ds_read_b128 v[220:223], v143 offset:3072
	s_waitcnt vmcnt(0)
	s_barrier
	s_waitcnt lgkmcnt(0)
	s_setprio 1
	v_mfma_f32_16x16x32_bf16 v[98:101], v[130:133], v[26:29], v[212:215]
	v_mfma_f32_16x16x32_bf16 v[26:29], v[208:211], v[26:29], v[168:171]
	v_mfma_f32_16x16x32_bf16 v[114:117], v[220:223], v[30:33], v[26:29]
	v_mfma_f32_16x16x32_bf16 v[26:29], v[130:133], v[42:45], v[86:89]
	v_mfma_f32_16x16x32_bf16 v[102:105], v[148:151], v[46:49], v[26:29]
	v_mfma_f32_16x16x32_bf16 v[26:29], v[208:211], v[42:45], v[82:85]
	v_mfma_f32_16x16x32_bf16 v[118:121], v[148:151], v[30:33], v[98:101]
	v_mfma_f32_16x16x32_bf16 v[98:101], v[220:223], v[46:49], v[26:29]
	v_mfma_f32_16x16x32_bf16 v[26:29], v[130:133], v[184:187], v[172:175]
	v_mfma_f32_16x16x32_bf16 v[86:89], v[148:151], v[188:191], v[26:29]
	v_mfma_f32_16x16x32_bf16 v[26:29], v[208:211], v[184:187], v[176:179]
	v_mfma_f32_16x16x32_bf16 v[82:85], v[220:223], v[188:191], v[26:29]
	v_mfma_f32_16x16x32_bf16 v[26:29], v[130:133], v[196:199], v[70:73]
	v_mfma_f32_16x16x32_bf16 v[70:73], v[148:151], v[204:207], v[26:29]
	v_mfma_f32_16x16x32_bf16 v[26:29], v[208:211], v[196:199], v[66:69]
	v_mfma_f32_16x16x32_bf16 v[66:69], v[220:223], v[204:207], v[26:29]
	s_setprio 0
	s_barrier
	ds_read_b128 v[168:171], v141 offset:49152
	ds_read_b128 v[140:143], v141 offset:50176
	ds_read_b128 v[172:175], v139 offset:49152
	ds_read_b128 v[176:179], v139 offset:50176
	ds_read_b128 v[184:187], v137 offset:49152
	ds_read_b128 v[136:139], v137 offset:50176
	ds_read_b128 v[188:191], v135 offset:49152
	ds_read_b128 v[196:199], v135 offset:50176
	s_barrier
	s_waitcnt lgkmcnt(0)
	s_setprio 1
	v_mfma_f32_16x16x32_bf16 v[26:29], v[10:13], v[168:171], v[62:65]
	v_mfma_f32_16x16x32_bf16 v[62:65], v[14:17], v[140:143], v[26:29]
	v_mfma_f32_16x16x32_bf16 v[26:29], v[180:183], v[168:171], v[58:61]
	v_mfma_f32_16x16x32_bf16 v[58:61], v[144:147], v[140:143], v[26:29]
	v_mfma_f32_16x16x32_bf16 v[26:29], v[10:13], v[172:175], v[54:57]
	v_mfma_f32_16x16x32_bf16 v[46:49], v[14:17], v[176:179], v[26:29]
	v_mfma_f32_16x16x32_bf16 v[26:29], v[180:183], v[172:175], v[50:53]
	v_mfma_f32_16x16x32_bf16 v[42:45], v[144:147], v[176:179], v[26:29]
	v_mfma_f32_16x16x32_bf16 v[26:29], v[10:13], v[184:187], v[200:203]
	v_mfma_f32_16x16x32_bf16 v[10:13], v[10:13], v[188:191], v[38:41]
	v_mfma_f32_16x16x32_bf16 v[30:33], v[14:17], v[136:139], v[26:29]
	v_mfma_f32_16x16x32_bf16 v[26:29], v[180:183], v[184:187], v[216:219]
	v_mfma_f32_16x16x32_bf16 v[14:17], v[14:17], v[196:199], v[10:13]
	v_mfma_f32_16x16x32_bf16 v[10:13], v[180:183], v[188:191], v[34:37]
	v_mfma_f32_16x16x32_bf16 v[26:29], v[144:147], v[136:139], v[26:29]
	v_mfma_f32_16x16x32_bf16 v[10:13], v[144:147], v[196:199], v[10:13]
	s_setprio 0
	s_setprio 1
	v_mfma_f32_16x16x32_bf16 v[34:37], v[130:133], v[168:171], v[152:155]
	v_mfma_f32_16x16x32_bf16 v[54:57], v[148:151], v[140:143], v[34:37]
	v_mfma_f32_16x16x32_bf16 v[34:37], v[208:211], v[168:171], v[156:159]
	v_mfma_f32_16x16x32_bf16 v[18:21], v[208:211], v[172:175], v[18:21]
	v_mfma_f32_16x16x32_bf16 v[50:53], v[220:223], v[140:143], v[34:37]
	v_mfma_f32_16x16x32_bf16 v[22:25], v[130:133], v[172:175], v[22:25]
	v_mfma_f32_16x16x32_bf16 v[34:37], v[220:223], v[176:179], v[18:21]
	v_mfma_f32_16x16x32_bf16 v[18:21], v[130:133], v[184:187], v[160:163]
	v_mfma_f32_16x16x32_bf16 v[38:41], v[148:151], v[176:179], v[22:25]
	v_mfma_f32_16x16x32_bf16 v[22:25], v[148:151], v[136:139], v[18:21]
	v_mfma_f32_16x16x32_bf16 v[18:21], v[208:211], v[184:187], v[164:167]
	v_mfma_f32_16x16x32_bf16 v[6:9], v[130:133], v[188:191], v[6:9]
	v_mfma_f32_16x16x32_bf16 v[2:5], v[208:211], v[188:191], v[2:5]
	v_mfma_f32_16x16x32_bf16 v[18:21], v[220:223], v[136:139], v[18:21]
	v_mfma_f32_16x16x32_bf16 v[6:9], v[148:151], v[196:199], v[6:9]
	v_mfma_f32_16x16x32_bf16 v[2:5], v[220:223], v[196:199], v[2:5]
	s_setprio 0
	v_cmp_gt_u32_e32 vcc, s30, v1
	s_barrier
	s_and_saveexec_b64 s[0:1], vcc
	s_cbranch_execz .LBB0_623
	s_barrier

; __global__ __launch_bounds__(NTHR, 2) void k_mega(Params p) {
;   extern __shared__ __attribute__((aligned(16))) char shm[];
;   cg::grid_group grid = cg::this_grid();
;   unsigned* barw = (unsigned*)(p.ws + OFF_BAR);
;   const int wv = __builtin_amdgcn_readfirstlane(threadIdx.x >> 6);
	.amdhsa_kernel _Z6k_mega6Params
		.amdhsa_group_segment_fixed_size 0
		.amdhsa_private_segment_fixed_size 0
		.amdhsa_kernarg_size 368
		.amdhsa_user_sgpr_count 2
		.amdhsa_user_sgpr_dispatch_ptr 0
		.amdhsa_user_sgpr_queue_ptr 0
		.amdhsa_user_sgpr_kernarg_segment_ptr 1
		.amdhsa_user_sgpr_dispatch_id 0
		.amdhsa_user_sgpr_kernarg_preload_length 0
		.amdhsa_user_sgpr_kernarg_preload_offset 0
		.amdhsa_user_sgpr_private_segment_size 0
		.amdhsa_uses_dynamic_stack 0
		.amdhsa_enable_private_segment 0
		.amdhsa_system_sgpr_workgroup_id_x 1
		.amdhsa_system_sgpr_workgroup_id_y 0
		.amdhsa_system_sgpr_workgroup_id_z 0
		.amdhsa_system_sgpr_workgroup_info 0
		.amdhsa_system_vgpr_workitem_id 2
		.amdhsa_next_free_vgpr 255
		.amdhsa_next_free_sgpr 99
		.amdhsa_accum_offset 256
		.amdhsa_reserve_vcc 1
		.amdhsa_float_round_mode_32 0
		.amdhsa_float_round_mode_16_64 0
		.amdhsa_float_denorm_mode_32 3
		.amdhsa_float_denorm_mode_16_64 3
		.amdhsa_dx10_clamp 1
		.amdhsa_ieee_mode 1
		.amdhsa_fp16_overflow 0
		.amdhsa_tg_split 0
		.amdhsa_exception_fp_ieee_invalid_op 0
		.amdhsa_exception_fp_denorm_src 0
		.amdhsa_exception_fp_ieee_div_zero 0
		.amdhsa_exception_fp_ieee_overflow 0
		.amdhsa_exception_fp_ieee_underflow 0
		.amdhsa_exception_fp_ieee_inexact 0
		.amdhsa_exception_int_div_zero 0
	.end_amdhsa_kernel
